# NSA sel branch: whole-query (lane) masking variant for non-diagonal blocks; GEMM tile prologue spurious vmcnt(0) removed
# speedup vs baseline: 1.1868x; 1.0075x over previous
; template <int DH, int NQ, int LDK, class MaskF>
; DEVI void attn_qk(const u16* sK, const bf16x8 (&qf)[NQ][DH / 32], f32x4 (&o)[NQ][DH / 16], float (&m)[NQ], float (&l)[NQ],
;                   float c2, int lane, MaskF valid, bf16x8 (&pb)[NQ][2]) {
;   const int col = lane & 15, quad = lane >> 4;
;   f32x4 s[NQ][4];
;   __builtin_amdgcn_s_setprio(1);
; #pragma unroll
;   for (int kt = 0; kt < 4; ++kt) {
; #pragma unroll
;     for (int qt = 0; qt < NQ; ++qt) s[qt][kt] = f32x4{0.f, 0.f, 0.f, 0.f};
; #pragma unroll
;     for (int ks = 0; ks < DH / 32; ++ks) {
;       const bf16x8 kf = *(const bf16x8*)(sK + (16 * kt + col) * LDK + 32 * ks + 8 * quad);
; #pragma unroll
;       for (int qt = 0; qt < NQ; ++qt) s[qt][kt] = mfma16(kf, qf[qt][ks], s[qt][kt]);
;     }
;   }
;   __builtin_amdgcn_s_setprio(0);
; #pragma unroll
;   for (int qt = 0; qt < NQ; ++qt) {
;     float mx = -1e30f;
; #pragma unroll
;     for (int kt = 0; kt < 4; ++kt)
; #pragma unroll
;       for (int r = 0; r < 4; ++r) {
;         const bool v = valid(qt, 16 * kt + 4 * quad + r);
;         const float sv = v ? s[qt][kt][r] : -1e30f;
;         s[qt][kt][r] = sv;
;         mx = fmaxf(mx, sv);
;       }
;     mx = fmaxf(mx, __shfl_xor(mx, 16));
;     mx = fmaxf(mx, __shfl_xor(mx, 32));
;     const float mn = fmaxf(m[qt], mx);
;     const float alpha = fexp2((m[qt] - mn) * c2);
;     m[qt] = mn;
;     const float mc = fmaxf(mn, -1e20f) * c2;
;     float ps = 0.f;
; #pragma unroll
;     for (int kt = 0; kt < 4; ++kt)
; #pragma unroll
;       for (int r = 0; r < 4; ++r) {
;         const float pv = fexp2(__builtin_fmaf(s[qt][kt][r], c2, -mc));
;         ps += pv;
;         s[qt][kt][r] = pv;
;       }
;     l[qt] = l[qt] * alpha + ps;
; #pragma unroll
;     for (int dt = 0; dt < DH / 16; ++dt) o[qt][dt] *= alpha;
; #pragma unroll
;     for (int kk = 0; kk < 2; ++kk) {
;       union { bf16x8 v; unsigned u[4]; } cv;
;       cv.u[0] = pack2(s[qt][2 * kk][0], s[qt][2 * kk][1]);
;       cv.u[1] = pack2(s[qt][2 * kk][2], s[qt][2 * kk][3]);
; DEVI void phase_nsa(const Params& p, unsigned char* smem) {
;     ...
;         const int lim0 = ((sm[0] >> kb) & 1u) ? tq[0] : -1, lim1 = ((sm[1] >> kb) & 1u) ? tq[1] : -1;
;         attn_tile<64, 2, 72, 72>(sK, sVt, qf, o, m, l, c2, lane, [&](int qt, int kl) {
;           return (kb * 64 + kl) <= (qt ? lim1 : lim0);
;         });
.Lp4_sel_nq3:
	s_lshl_b32 s30, s26, 6
	s_lshr_b32 s22, s29, s26
	s_and_b32 s22, s22, 1
	s_add_u32 s23, s30, 63
	s_cmp_le_u32 s23, s19
	s_cselect_b32 s23, 1, 0
	s_cselect_b32 s24, s22, 0
	s_cmp_eq_u32 s24, 0
	s_cbranch_scc1 .Lp4_sel_masked
	v_add_u32_e32 v227, s46, v235
	v_add_u32_e32 v228, s46, v236
	v_add_u32_e32 v231, s46, v237
	v_add_u32_e32 v233, s46, v239
	v_add_u32_e32 v232, s46, v238
	v_add_u32_e32 v234, s46, v240
	ds_read_b128 v[112:115], v227
	ds_read_b128 v[116:119], v228
	ds_read_b128 v[120:123], v227 offset:2048
	ds_read_b128 v[124:127], v228 offset:2048
	ds_read_b128 v[128:131], v227 offset:4096
	ds_read_b128 v[132:135], v228 offset:4096
	ds_read_b128 v[136:139], v227 offset:6144
	ds_read_b128 v[140:143], v228 offset:6144
	s_waitcnt lgkmcnt(7)
	v_mfma_f32_16x16x32_bf16 v[80:83], v[112:115], v[0:3], 0
	v_mfma_f32_16x16x32_bf16 v[96:99], v[112:115], v[8:11], 0
	s_waitcnt lgkmcnt(6)
	v_mfma_f32_16x16x32_bf16 v[80:83], v[116:119], v[4:7], v[80:83]
	v_mfma_f32_16x16x32_bf16 v[96:99], v[116:119], v[12:15], v[96:99]
	s_waitcnt lgkmcnt(5)
	v_mfma_f32_16x16x32_bf16 v[84:87], v[120:123], v[0:3], 0
	v_mfma_f32_16x16x32_bf16 v[100:103], v[120:123], v[8:11], 0
	s_waitcnt lgkmcnt(4)
	v_mfma_f32_16x16x32_bf16 v[84:87], v[124:127], v[4:7], v[84:87]
	v_mfma_f32_16x16x32_bf16 v[100:103], v[124:127], v[12:15], v[100:103]
	s_waitcnt lgkmcnt(3)
	v_mfma_f32_16x16x32_bf16 v[88:91], v[128:131], v[0:3], 0
	v_mfma_f32_16x16x32_bf16 v[104:107], v[128:131], v[8:11], 0
	s_waitcnt lgkmcnt(2)
	v_mfma_f32_16x16x32_bf16 v[88:91], v[132:135], v[4:7], v[88:91]
	v_mfma_f32_16x16x32_bf16 v[104:107], v[132:135], v[12:15], v[104:107]
	s_waitcnt lgkmcnt(1)
	v_mfma_f32_16x16x32_bf16 v[92:95], v[136:139], v[0:3], 0
	v_mfma_f32_16x16x32_bf16 v[108:111], v[136:139], v[8:11], 0
	s_waitcnt lgkmcnt(0)
	v_mfma_f32_16x16x32_bf16 v[92:95], v[140:143], v[4:7], v[92:95]
	v_mfma_f32_16x16x32_bf16 v[108:111], v[140:143], v[12:15], v[108:111]
	ds_read_b64 v[112:113], v231 offset:0
	ds_read_b64 v[114:115], v233 offset:0
	ds_read_b64 v[116:117], v232 offset:0
	ds_read_b64 v[118:119], v234 offset:0
	ds_read_b64 v[120:121], v231 offset:2048
	ds_read_b64 v[122:123], v233 offset:2048
	ds_read_b64 v[124:125], v232 offset:2048
	ds_read_b64 v[126:127], v234 offset:2048
	s_nop 3
	v_max3_f32 v215, v80, v81, v82
	v_max3_f32 v215, v215, v83, v84
	v_max3_f32 v215, v215, v85, v86
	v_max3_f32 v215, v215, v87, v88
	v_max3_f32 v215, v215, v89, v90
	v_max3_f32 v215, v215, v91, v92
	v_max3_f32 v215, v215, v93, v94
	v_max_f32_e32 v215, v95, v215
	ds_bpermute_b32 v217, v195, v215
	s_waitcnt lgkmcnt(0)
	v_max_f32_e32 v215, v217, v215
	v_mov_b32_e32 v217, v215
	v_mov_b32_e32 v218, v215
	s_nop 1
	v_permlane32_swap_b32_e32 v217, v218
	v_max_f32_e32 v215, v217, v218
	v_max_f32_e32 v219, v182, v215
	v_sub_f32_e32 v216, v182, v219
	v_mul_f32_e32 v216, v200, v216
	v_exp_f32_e32 v216, v216
	v_mov_b32_e32 v182, v219
	v_max_f32_e32 v220, 0xe0ad78ec, v219
	v_mul_f32_e32 v220, 0xbe38aa3b, v220
	v_fma_f32 v80, v80, v200, v220
	v_exp_f32_e32 v80, v80
	v_fma_f32 v81, v81, v200, v220
	v_exp_f32_e32 v81, v81
	v_fma_f32 v82, v82, v200, v220
	v_exp_f32_e32 v82, v82
	v_fma_f32 v83, v83, v200, v220
	v_exp_f32_e32 v83, v83
	v_fma_f32 v84, v84, v200, v220
	v_exp_f32_e32 v84, v84
	v_fma_f32 v85, v85, v200, v220
	v_exp_f32_e32 v85, v85
	v_fma_f32 v86, v86, v200, v220
	v_exp_f32_e32 v86, v86
	v_fma_f32 v87, v87, v200, v220
	v_exp_f32_e32 v87, v87
	v_fma_f32 v88, v88, v200, v220
	v_exp_f32_e32 v88, v88
	v_fma_f32 v89, v89, v200, v220
	v_exp_f32_e32 v89, v89
	v_fma_f32 v90, v90, v200, v220
	v_exp_f32_e32 v90, v90
	v_fma_f32 v91, v91, v200, v220
	v_exp_f32_e32 v91, v91
	v_fma_f32 v92, v92, v200, v220
	v_exp_f32_e32 v92, v92
	v_fma_f32 v93, v93, v200, v220
	v_exp_f32_e32 v93, v93
	v_fma_f32 v94, v94, v200, v220
	v_exp_f32_e32 v94, v94
	v_fma_f32 v95, v95, v200, v220
	v_exp_f32_e32 v95, v95
	s_nop 0
	v_add_f32_e32 v221, v80, v81
	v_add_f32_e32 v221, v82, v221
	v_add_f32_e32 v221, v83, v221
	v_add_f32_e32 v221, v84, v221
	v_add_f32_e32 v221, v85, v221
	v_add_f32_e32 v221, v86, v221
	v_add_f32_e32 v221, v87, v221
	v_add_f32_e32 v221, v88, v221
	v_add_f32_e32 v221, v89, v221
	v_add_f32_e32 v221, v90, v221
	v_add_f32_e32 v221, v91, v221
	v_add_f32_e32 v221, v92, v221
	v_add_f32_e32 v221, v93, v221
	v_add_f32_e32 v221, v94, v221
	v_add_f32_e32 v221, v95, v221
	v_mul_f32_e32 v16, v216, v16
	v_mul_f32_e32 v17, v216, v17
	v_mul_f32_e32 v18, v216, v18
	v_mul_f32_e32 v19, v216, v19
	v_mul_f32_e32 v20, v216, v20
	v_mul_f32_e32 v21, v216, v21
	v_mul_f32_e32 v22, v216, v22
	v_mul_f32_e32 v23, v216, v23
	v_mul_f32_e32 v24, v216, v24
	v_mul_f32_e32 v25, v216, v25
	v_mul_f32_e32 v26, v216, v26
	v_mul_f32_e32 v27, v216, v27
	v_mul_f32_e32 v28, v216, v28
	v_mul_f32_e32 v29, v216, v29
	v_mul_f32_e32 v30, v216, v30
	v_mul_f32_e32 v31, v216, v31
	v_fma_f32 v184, v184, v216, v221
	v_cvt_pk_bf16_f32 v144, v80, v81
	v_cvt_pk_bf16_f32 v145, v82, v83
	v_cvt_pk_bf16_f32 v146, v84, v85
	v_cvt_pk_bf16_f32 v147, v86, v87
	v_cvt_pk_bf16_f32 v148, v88, v89
	v_cvt_pk_bf16_f32 v149, v90, v91
	v_cvt_pk_bf16_f32 v150, v92, v93
	v_cvt_pk_bf16_f32 v151, v94, v95
	v_max3_f32 v215, v96, v97, v98
	v_max3_f32 v215, v215, v99, v100
	v_max3_f32 v215, v215, v101, v102
	v_max3_f32 v215, v215, v103, v104
	v_max3_f32 v215, v215, v105, v106
	v_max3_f32 v215, v215, v107, v108
	v_max3_f32 v215, v215, v109, v110
	v_max_f32_e32 v215, v111, v215
	ds_bpermute_b32 v217, v195, v215
	s_waitcnt lgkmcnt(0)
; DEVI unsigned pack2(float a, float b) { return (unsigned)f2bf(a) | ((unsigned)f2bf(b) << 16); }
; template <int DH, int NQ, int LDK, class MaskF>
; DEVI void attn_qk(const u16* sK, const bf16x8 (&qf)[NQ][DH / 32], f32x4 (&o)[NQ][DH / 16], float (&m)[NQ], float (&l)[NQ],
;                   float c2, int lane, MaskF valid, bf16x8 (&pb)[NQ][2]) {
;     ...
;     mx = fmaxf(mx, __shfl_xor(mx, 16));
;     mx = fmaxf(mx, __shfl_xor(mx, 32));
;     const float mn = fmaxf(m[qt], mx);
;     const float alpha = fexp2((m[qt] - mn) * c2);
;     m[qt] = mn;
;     const float mc = fmaxf(mn, -1e20f) * c2;
;     float ps = 0.f;
; #pragma unroll
;     for (int kt = 0; kt < 4; ++kt)
; #pragma unroll
;       for (int r = 0; r < 4; ++r) {
;         const float pv = fexp2(__builtin_fmaf(s[qt][kt][r], c2, -mc));
;         ps += pv;
;         s[qt][kt][r] = pv;
;       }
;     l[qt] = l[qt] * alpha + ps;
; #pragma unroll
;     for (int dt = 0; dt < DH / 16; ++dt) o[qt][dt] *= alpha;
; #pragma unroll
;     for (int kk = 0; kk < 2; ++kk) {
;       union { bf16x8 v; unsigned u[4]; } cv;
;       cv.u[0] = pack2(s[qt][2 * kk][0], s[qt][2 * kk][1]);
;       cv.u[1] = pack2(s[qt][2 * kk][2], s[qt][2 * kk][3]);
;       cv.u[2] = pack2(s[qt][2 * kk + 1][0], s[qt][2 * kk + 1][1]);
;       cv.u[3] = pack2(s[qt][2 * kk + 1][2], s[qt][2 * kk + 1][3]);
;       pb[qt][kk] = cv.v;
;     }
;   }
; }
; template <int DH, int NQ, int LDV>
; DEVI void attn_pv(const u16* sVt, const bf16x8 (&pb)[NQ][2], f32x4 (&o)[NQ][DH / 16], int lane) {
;   const int col = lane & 15, quad = lane >> 4;
;   __builtin_amdgcn_s_setprio(1);
; #pragma unroll
;   for (int dt = 0; dt < DH / 16; ++dt) {
; #pragma unroll
;     for (int kk = 0; kk < 2; ++kk) {
;       union { bf16x8 v; uint2 h[2]; } cv;
;       cv.h[0] = *(const uint2*)(sVt + (16 * dt + col) * LDV + 32 * kk + 4 * quad);
;       cv.h[1] = *(const uint2*)(sVt + (16 * dt + col) * LDV + 32 * kk + 16 + 4 * quad);
; #pragma unroll
;       for (int qt = 0; qt < NQ; ++qt) o[qt][dt] = mfma16(cv.v, pb[qt][kk], o[qt][dt]);
;     }
;   }
;   __builtin_amdgcn_s_setprio(0);
; DEVI void phase_nsa(const Params& p, unsigned char* smem) {
;     ...
;         const int lim0 = ((sm[0] >> kb) & 1u) ? tq[0] : -1, lim1 = ((sm[1] >> kb) & 1u) ? tq[1] : -1;
;         attn_tile<64, 2, 72, 72>(sK, sVt, qf, o, m, l, c2, lane, [&](int qt, int kl) {
;           return (kb * 64 + kl) <= (qt ? lim1 : lim0);
	v_max_f32_e32 v215, v217, v215
	v_mov_b32_e32 v217, v215
	v_mov_b32_e32 v218, v215
	s_nop 1
	v_permlane32_swap_b32_e32 v217, v218
	v_max_f32_e32 v215, v217, v218
	v_max_f32_e32 v219, v183, v215
	v_sub_f32_e32 v216, v183, v219
	v_mul_f32_e32 v216, v200, v216
	v_exp_f32_e32 v216, v216
	v_mov_b32_e32 v183, v219
	v_max_f32_e32 v220, 0xe0ad78ec, v219
	v_mul_f32_e32 v220, 0xbe38aa3b, v220
	v_fma_f32 v96, v96, v200, v220
	v_exp_f32_e32 v96, v96
	v_fma_f32 v97, v97, v200, v220
	v_exp_f32_e32 v97, v97
	v_fma_f32 v98, v98, v200, v220
	v_exp_f32_e32 v98, v98
	v_fma_f32 v99, v99, v200, v220
	v_exp_f32_e32 v99, v99
	v_fma_f32 v100, v100, v200, v220
	v_exp_f32_e32 v100, v100
	v_fma_f32 v101, v101, v200, v220
	v_exp_f32_e32 v101, v101
	v_fma_f32 v102, v102, v200, v220
	v_exp_f32_e32 v102, v102
	v_fma_f32 v103, v103, v200, v220
	v_exp_f32_e32 v103, v103
	v_fma_f32 v104, v104, v200, v220
	v_exp_f32_e32 v104, v104
	v_fma_f32 v105, v105, v200, v220
	v_exp_f32_e32 v105, v105
	v_fma_f32 v106, v106, v200, v220
	v_exp_f32_e32 v106, v106
	v_fma_f32 v107, v107, v200, v220
	v_exp_f32_e32 v107, v107
	v_fma_f32 v108, v108, v200, v220
	v_exp_f32_e32 v108, v108
	v_fma_f32 v109, v109, v200, v220
	v_exp_f32_e32 v109, v109
	v_fma_f32 v110, v110, v200, v220
	v_exp_f32_e32 v110, v110
	v_fma_f32 v111, v111, v200, v220
	v_exp_f32_e32 v111, v111
	s_nop 0
	v_add_f32_e32 v221, v96, v97
	v_add_f32_e32 v221, v98, v221
	v_add_f32_e32 v221, v99, v221
	v_add_f32_e32 v221, v100, v221
	v_add_f32_e32 v221, v101, v221
	v_add_f32_e32 v221, v102, v221
	v_add_f32_e32 v221, v103, v221
	v_add_f32_e32 v221, v104, v221
	v_add_f32_e32 v221, v105, v221
	v_add_f32_e32 v221, v106, v221
	v_add_f32_e32 v221, v107, v221
	v_add_f32_e32 v221, v108, v221
	v_add_f32_e32 v221, v109, v221
	v_add_f32_e32 v221, v110, v221
	v_add_f32_e32 v221, v111, v221
	v_mul_f32_e32 v32, v216, v32
	v_mul_f32_e32 v33, v216, v33
	v_mul_f32_e32 v34, v216, v34
	v_mul_f32_e32 v35, v216, v35
	v_mul_f32_e32 v36, v216, v36
	v_mul_f32_e32 v37, v216, v37
	v_mul_f32_e32 v38, v216, v38
	v_mul_f32_e32 v39, v216, v39
	v_mul_f32_e32 v40, v216, v40
	v_mul_f32_e32 v41, v216, v41
	v_mul_f32_e32 v42, v216, v42
	v_mul_f32_e32 v43, v216, v43
	v_mul_f32_e32 v44, v216, v44
	v_mul_f32_e32 v45, v216, v45
	v_mul_f32_e32 v46, v216, v46
	v_mul_f32_e32 v47, v216, v47
	v_fma_f32 v185, v185, v216, v221
	v_cvt_pk_bf16_f32 v152, v96, v97
	v_cvt_pk_bf16_f32 v153, v98, v99
	v_cvt_pk_bf16_f32 v154, v100, v101
	v_cvt_pk_bf16_f32 v155, v102, v103
	v_cvt_pk_bf16_f32 v156, v104, v105
	v_cvt_pk_bf16_f32 v157, v106, v107
	v_cvt_pk_bf16_f32 v158, v108, v109
	v_cvt_pk_bf16_f32 v159, v110, v111
	ds_read_b64 v[128:129], v231 offset:4096
	ds_read_b64 v[130:131], v233 offset:4096
	ds_read_b64 v[132:133], v232 offset:4096
	ds_read_b64 v[134:135], v234 offset:4096
	ds_read_b64 v[136:137], v231 offset:6144
	ds_read_b64 v[138:139], v233 offset:6144
	ds_read_b64 v[140:141], v232 offset:6144
	ds_read_b64 v[142:143], v234 offset:6144
	s_waitcnt lgkmcnt(8)
	v_mfma_f32_16x16x32_bf16 v[16:19], v[112:115], v[144:147], v[16:19]
	v_mfma_f32_16x16x32_bf16 v[32:35], v[112:115], v[152:155], v[32:35]
	v_mfma_f32_16x16x32_bf16 v[16:19], v[116:119], v[148:151], v[16:19]
	v_mfma_f32_16x16x32_bf16 v[32:35], v[116:119], v[156:159], v[32:35]
	v_mfma_f32_16x16x32_bf16 v[20:23], v[120:123], v[144:147], v[20:23]
	v_mfma_f32_16x16x32_bf16 v[36:39], v[120:123], v[152:155], v[36:39]
	v_mfma_f32_16x16x32_bf16 v[20:23], v[124:127], v[148:151], v[20:23]
	v_mfma_f32_16x16x32_bf16 v[36:39], v[124:127], v[156:159], v[36:39]
	s_waitcnt lgkmcnt(0)
	v_mfma_f32_16x16x32_bf16 v[24:27], v[128:131], v[144:147], v[24:27]
	v_mfma_f32_16x16x32_bf16 v[40:43], v[128:131], v[152:155], v[40:43]
	v_mfma_f32_16x16x32_bf16 v[24:27], v[132:135], v[148:151], v[24:27]
	v_mfma_f32_16x16x32_bf16 v[40:43], v[132:135], v[156:159], v[40:43]
	v_mfma_f32_16x16x32_bf16 v[28:31], v[136:139], v[144:147], v[28:31]
	v_mfma_f32_16x16x32_bf16 v[44:47], v[136:139], v[152:155], v[44:47]
	v_mfma_f32_16x16x32_bf16 v[28:31], v[140:143], v[148:151], v[28:31]
	v_mfma_f32_16x16x32_bf16 v[44:47], v[140:143], v[156:159], v[44:47]
	s_branch .Lp4_sel_next
.Lp4_sel_masked:
	s_cmp_eq_u32 s23, 0
	s_cbranch_scc1 .Lp4_sel_elem
	v_lshrrev_b32_e32 v215, s26, v188
	v_and_b32_e32 v215, 1, v215
	v_cmp_eq_u32_e64 s[36:37], 1, v215
	v_lshrrev_b32_e32 v215, s26, v189
	v_and_b32_e32 v215, 1, v215
	v_cmp_eq_u32_e64 s[38:39], 1, v215
	v_add_u32_e32 v227, s46, v235
	v_add_u32_e32 v228, s46, v236
	v_add_u32_e32 v231, s46, v237
	v_add_u32_e32 v233, s46, v239
	v_add_u32_e32 v232, s46, v238
	v_add_u32_e32 v234, s46, v240
	ds_read_b128 v[112:115], v227
	ds_read_b128 v[116:119], v228
	ds_read_b128 v[120:123], v227 offset:2048
	ds_read_b128 v[124:127], v228 offset:2048
	ds_read_b128 v[128:131], v227 offset:4096
	ds_read_b128 v[132:135], v228 offset:4096
	ds_read_b128 v[136:139], v227 offset:6144
	ds_read_b128 v[140:143], v228 offset:6144
	s_waitcnt lgkmcnt(7)
	v_mfma_f32_16x16x32_bf16 v[80:83], v[112:115], v[0:3], 0
	v_mfma_f32_16x16x32_bf16 v[96:99], v[112:115], v[8:11], 0
	s_waitcnt lgkmcnt(6)
	v_mfma_f32_16x16x32_bf16 v[80:83], v[116:119], v[4:7], v[80:83]
	v_mfma_f32_16x16x32_bf16 v[96:99], v[116:119], v[12:15], v[96:99]
	s_waitcnt lgkmcnt(5)
	v_mfma_f32_16x16x32_bf16 v[84:87], v[120:123], v[0:3], 0
	v_mfma_f32_16x16x32_bf16 v[100:103], v[120:123], v[8:11], 0
	s_waitcnt lgkmcnt(4)
	v_mfma_f32_16x16x32_bf16 v[84:87], v[124:127], v[4:7], v[84:87]
	v_mfma_f32_16x16x32_bf16 v[100:103], v[124:127], v[12:15], v[100:103]
	s_waitcnt lgkmcnt(3)
	v_mfma_f32_16x16x32_bf16 v[88:91], v[128:131], v[0:3], 0
	v_mfma_f32_16x16x32_bf16 v[104:107], v[128:131], v[8:11], 0
	s_waitcnt lgkmcnt(2)
; DEVI unsigned pack2(float a, float b) { return (unsigned)f2bf(a) | ((unsigned)f2bf(b) << 16); }
; DEVI float fexp2(float x) { return __builtin_amdgcn_exp2f(x); }
; template <int DH, int NQ, int LDK, class MaskF>
; DEVI void attn_qk(const u16* sK, const bf16x8 (&qf)[NQ][DH / 32], f32x4 (&o)[NQ][DH / 16], float (&m)[NQ], float (&l)[NQ],
;                   float c2, int lane, MaskF valid, bf16x8 (&pb)[NQ][2]) {
;     ...
;   for (int qt = 0; qt < NQ; ++qt) {
;     float mx = -1e30f;
; #pragma unroll
;     for (int kt = 0; kt < 4; ++kt)
; #pragma unroll
;       for (int r = 0; r < 4; ++r) {
;         const bool v = valid(qt, 16 * kt + 4 * quad + r);
;         const float sv = v ? s[qt][kt][r] : -1e30f;
;         s[qt][kt][r] = sv;
;         mx = fmaxf(mx, sv);
;       }
;     mx = fmaxf(mx, __shfl_xor(mx, 16));
;     mx = fmaxf(mx, __shfl_xor(mx, 32));
;     const float mn = fmaxf(m[qt], mx);
;     const float alpha = fexp2((m[qt] - mn) * c2);
;     m[qt] = mn;
;     const float mc = fmaxf(mn, -1e20f) * c2;
;     float ps = 0.f;
; #pragma unroll
;     for (int kt = 0; kt < 4; ++kt)
; #pragma unroll
;       for (int r = 0; r < 4; ++r) {
;         const float pv = fexp2(__builtin_fmaf(s[qt][kt][r], c2, -mc));
;         ps += pv;
;         s[qt][kt][r] = pv;
;       }
;     l[qt] = l[qt] * alpha + ps;
; #pragma unroll
;     for (int dt = 0; dt < DH / 16; ++dt) o[qt][dt] *= alpha;
; #pragma unroll
;     for (int kk = 0; kk < 2; ++kk) {
;       union { bf16x8 v; unsigned u[4]; } cv;
;       cv.u[0] = pack2(s[qt][2 * kk][0], s[qt][2 * kk][1]);
;       cv.u[1] = pack2(s[qt][2 * kk][2], s[qt][2 * kk][3]);
;       cv.u[2] = pack2(s[qt][2 * kk + 1][0], s[qt][2 * kk + 1][1]);
;       cv.u[3] = pack2(s[qt][2 * kk + 1][2], s[qt][2 * kk + 1][3]);
;       pb[qt][kk] = cv.v;
;     }
;   }
	v_mfma_f32_16x16x32_bf16 v[88:91], v[132:135], v[4:7], v[88:91]
	v_mfma_f32_16x16x32_bf16 v[104:107], v[132:135], v[12:15], v[104:107]
	s_waitcnt lgkmcnt(1)
	v_mfma_f32_16x16x32_bf16 v[92:95], v[136:139], v[0:3], 0
	v_mfma_f32_16x16x32_bf16 v[108:111], v[136:139], v[8:11], 0
	s_waitcnt lgkmcnt(0)
	v_mfma_f32_16x16x32_bf16 v[92:95], v[140:143], v[4:7], v[92:95]
	v_mfma_f32_16x16x32_bf16 v[108:111], v[140:143], v[12:15], v[108:111]
	ds_read_b64 v[112:113], v231 offset:0
	ds_read_b64 v[114:115], v233 offset:0
	ds_read_b64 v[116:117], v232 offset:0
	ds_read_b64 v[118:119], v234 offset:0
	ds_read_b64 v[120:121], v231 offset:2048
	ds_read_b64 v[122:123], v233 offset:2048
	ds_read_b64 v[124:125], v232 offset:2048
	ds_read_b64 v[126:127], v234 offset:2048
	s_nop 3
	v_max3_f32 v215, v80, v81, v82
	v_max3_f32 v215, v215, v83, v84
	v_max3_f32 v215, v215, v85, v86
	v_max3_f32 v215, v215, v87, v88
	v_max3_f32 v215, v215, v89, v90
	v_max3_f32 v215, v215, v91, v92
	v_max3_f32 v215, v215, v93, v94
	v_max_f32_e32 v215, v95, v215
	v_cndmask_b32_e64 v215, v230, v215, s[36:37]
	ds_bpermute_b32 v217, v195, v215
	s_waitcnt lgkmcnt(0)
	v_max_f32_e32 v215, v217, v215
	v_mov_b32_e32 v217, v215
	v_mov_b32_e32 v218, v215
	s_nop 1
	v_permlane32_swap_b32_e32 v217, v218
	v_max_f32_e32 v215, v217, v218
	v_max_f32_e32 v219, v182, v215
	v_sub_f32_e32 v216, v182, v219
	v_mul_f32_e32 v216, v200, v216
	v_exp_f32_e32 v216, v216
	v_mov_b32_e32 v182, v219
	v_max_f32_e32 v220, 0xe0ad78ec, v219
	v_mul_f32_e32 v220, 0xbe38aa3b, v220
	v_mov_b32_e32 v224, 0
	v_cndmask_b32_e64 v224, v224, v200, s[36:37]
	v_cndmask_b32_e64 v220, v230, v220, s[36:37]
	v_fma_f32 v80, v80, v224, v220
	v_exp_f32_e32 v80, v80
	v_fma_f32 v81, v81, v224, v220
	v_exp_f32_e32 v81, v81
	v_fma_f32 v82, v82, v224, v220
	v_exp_f32_e32 v82, v82
	v_fma_f32 v83, v83, v224, v220
	v_exp_f32_e32 v83, v83
	v_fma_f32 v84, v84, v224, v220
	v_exp_f32_e32 v84, v84
	v_fma_f32 v85, v85, v224, v220
	v_exp_f32_e32 v85, v85
	v_fma_f32 v86, v86, v224, v220
	v_exp_f32_e32 v86, v86
	v_fma_f32 v87, v87, v224, v220
	v_exp_f32_e32 v87, v87
	v_fma_f32 v88, v88, v224, v220
	v_exp_f32_e32 v88, v88
	v_fma_f32 v89, v89, v224, v220
	v_exp_f32_e32 v89, v89
	v_fma_f32 v90, v90, v224, v220
	v_exp_f32_e32 v90, v90
	v_fma_f32 v91, v91, v224, v220
	v_exp_f32_e32 v91, v91
	v_fma_f32 v92, v92, v224, v220
	v_exp_f32_e32 v92, v92
	v_fma_f32 v93, v93, v224, v220
	v_exp_f32_e32 v93, v93
	v_fma_f32 v94, v94, v224, v220
	v_exp_f32_e32 v94, v94
	v_fma_f32 v95, v95, v224, v220
	v_exp_f32_e32 v95, v95
	s_nop 0
	v_add_f32_e32 v221, v80, v81
	v_add_f32_e32 v221, v82, v221
	v_add_f32_e32 v221, v83, v221
	v_add_f32_e32 v221, v84, v221
	v_add_f32_e32 v221, v85, v221
	v_add_f32_e32 v221, v86, v221
	v_add_f32_e32 v221, v87, v221
	v_add_f32_e32 v221, v88, v221
	v_add_f32_e32 v221, v89, v221
	v_add_f32_e32 v221, v90, v221
	v_add_f32_e32 v221, v91, v221
	v_add_f32_e32 v221, v92, v221
	v_add_f32_e32 v221, v93, v221
	v_add_f32_e32 v221, v94, v221
	v_add_f32_e32 v221, v95, v221
	v_mul_f32_e32 v16, v216, v16
	v_mul_f32_e32 v17, v216, v17
	v_mul_f32_e32 v18, v216, v18
	v_mul_f32_e32 v19, v216, v19
	v_mul_f32_e32 v20, v216, v20
	v_mul_f32_e32 v21, v216, v21
	v_mul_f32_e32 v22, v216, v22
	v_mul_f32_e32 v23, v216, v23
	v_mul_f32_e32 v24, v216, v24
	v_mul_f32_e32 v25, v216, v25
	v_mul_f32_e32 v26, v216, v26
	v_mul_f32_e32 v27, v216, v27
	v_mul_f32_e32 v28, v216, v28
	v_mul_f32_e32 v29, v216, v29
	v_mul_f32_e32 v30, v216, v30
	v_mul_f32_e32 v31, v216, v31
	v_fma_f32 v184, v184, v216, v221
	v_cvt_pk_bf16_f32 v144, v80, v81
	v_cvt_pk_bf16_f32 v145, v82, v83
	v_cvt_pk_bf16_f32 v146, v84, v85
	v_cvt_pk_bf16_f32 v147, v86, v87
	v_cvt_pk_bf16_f32 v148, v88, v89
	v_cvt_pk_bf16_f32 v149, v90, v91
	v_cvt_pk_bf16_f32 v150, v92, v93
	v_cvt_pk_bf16_f32 v151, v94, v95
	v_max3_f32 v215, v96, v97, v98
	v_max3_f32 v215, v215, v99, v100
	v_max3_f32 v215, v215, v101, v102
	v_max3_f32 v215, v215, v103, v104
	v_max3_f32 v215, v215, v105, v106
	v_max3_f32 v215, v215, v107, v108
	v_max3_f32 v215, v215, v109, v110
	v_max_f32_e32 v215, v111, v215
	v_cndmask_b32_e64 v215, v230, v215, s[38:39]
	ds_bpermute_b32 v217, v195, v215
	s_waitcnt lgkmcnt(0)
	v_max_f32_e32 v215, v217, v215
	v_mov_b32_e32 v217, v215
	v_mov_b32_e32 v218, v215
	s_nop 1
	v_permlane32_swap_b32_e32 v217, v218
	v_max_f32_e32 v215, v217, v218
	v_max_f32_e32 v219, v183, v215
	v_sub_f32_e32 v216, v183, v219
	v_mul_f32_e32 v216, v200, v216
	v_exp_f32_e32 v216, v216
	v_mov_b32_e32 v183, v219
	v_max_f32_e32 v220, 0xe0ad78ec, v219
	v_mul_f32_e32 v220, 0xbe38aa3b, v220
	v_mov_b32_e32 v224, 0
	v_cndmask_b32_e64 v224, v224, v200, s[38:39]
	v_cndmask_b32_e64 v220, v230, v220, s[38:39]
	v_fma_f32 v96, v96, v224, v220
	v_exp_f32_e32 v96, v96
	v_fma_f32 v97, v97, v224, v220
	v_exp_f32_e32 v97, v97
	v_fma_f32 v98, v98, v224, v220
	v_exp_f32_e32 v98, v98
	v_fma_f32 v99, v99, v224, v220
	v_exp_f32_e32 v99, v99
	v_fma_f32 v100, v100, v224, v220
	v_exp_f32_e32 v100, v100
	v_fma_f32 v101, v101, v224, v220
	v_exp_f32_e32 v101, v101
	v_fma_f32 v102, v102, v224, v220
	v_exp_f32_e32 v102, v102
	v_fma_f32 v103, v103, v224, v220
	v_exp_f32_e32 v103, v103
	v_fma_f32 v104, v104, v224, v220
	v_exp_f32_e32 v104, v104
	v_fma_f32 v105, v105, v224, v220
	v_exp_f32_e32 v105, v105
	v_fma_f32 v106, v106, v224, v220
	v_exp_f32_e32 v106, v106
	v_fma_f32 v107, v107, v224, v220
	v_exp_f32_e32 v107, v107
	v_fma_f32 v108, v108, v224, v220
	v_exp_f32_e32 v108, v108
	v_fma_f32 v109, v109, v224, v220
	v_exp_f32_e32 v109, v109
	v_fma_f32 v110, v110, v224, v220
	v_exp_f32_e32 v110, v110
	v_fma_f32 v111, v111, v224, v220
	v_exp_f32_e32 v111, v111
	s_nop 0
	v_add_f32_e32 v221, v96, v97
; DEVI unsigned pack2(float a, float b) { return (unsigned)f2bf(a) | ((unsigned)f2bf(b) << 16); }
; DEVI f32x4 mfma16(bf16x8 a, bf16x8 b, f32x4 c) { return __builtin_amdgcn_mfma_f32_16x16x32_bf16(a, b, c, 0, 0, 0); }
; template <int DH, int NQ, int LDK, class MaskF>
; DEVI void attn_qk(const u16* sK, const bf16x8 (&qf)[NQ][DH / 32], f32x4 (&o)[NQ][DH / 16], float (&m)[NQ], float (&l)[NQ],
;                   float c2, int lane, MaskF valid, bf16x8 (&pb)[NQ][2]) {
;     ...
;     l[qt] = l[qt] * alpha + ps;
; #pragma unroll
;     for (int dt = 0; dt < DH / 16; ++dt) o[qt][dt] *= alpha;
; #pragma unroll
;     for (int kk = 0; kk < 2; ++kk) {
;       union { bf16x8 v; unsigned u[4]; } cv;
;       cv.u[0] = pack2(s[qt][2 * kk][0], s[qt][2 * kk][1]);
;       cv.u[1] = pack2(s[qt][2 * kk][2], s[qt][2 * kk][3]);
;       cv.u[2] = pack2(s[qt][2 * kk + 1][0], s[qt][2 * kk + 1][1]);
;       cv.u[3] = pack2(s[qt][2 * kk + 1][2], s[qt][2 * kk + 1][3]);
;       pb[qt][kk] = cv.v;
;     }
;   }
; }
; template <int DH, int NQ, int LDV>
; DEVI void attn_pv(const u16* sVt, const bf16x8 (&pb)[NQ][2], f32x4 (&o)[NQ][DH / 16], int lane) {
;   const int col = lane & 15, quad = lane >> 4;
;   __builtin_amdgcn_s_setprio(1);
; #pragma unroll
;   for (int dt = 0; dt < DH / 16; ++dt) {
; #pragma unroll
;     for (int kk = 0; kk < 2; ++kk) {
;       union { bf16x8 v; uint2 h[2]; } cv;
;       cv.h[0] = *(const uint2*)(sVt + (16 * dt + col) * LDV + 32 * kk + 4 * quad);
;       cv.h[1] = *(const uint2*)(sVt + (16 * dt + col) * LDV + 32 * kk + 16 + 4 * quad);
; #pragma unroll
;       for (int qt = 0; qt < NQ; ++qt) o[qt][dt] = mfma16(cv.v, pb[qt][kk], o[qt][dt]);
;     }
;   }
;   __builtin_amdgcn_s_setprio(0);
; DEVI void phase_nsa(const Params& p, unsigned char* smem) {
;     ...
;         const int lim0 = ((sm[0] >> kb) & 1u) ? tq[0] : -1, lim1 = ((sm[1] >> kb) & 1u) ? tq[1] : -1;
;         attn_tile<64, 2, 72, 72>(sK, sVt, qf, o, m, l, c2, lane, [&](int qt, int kl) {
;           return (kb * 64 + kl) <= (qt ? lim1 : lim0);
	v_add_f32_e32 v221, v98, v221
	v_add_f32_e32 v221, v99, v221
	v_add_f32_e32 v221, v100, v221
	v_add_f32_e32 v221, v101, v221
	v_add_f32_e32 v221, v102, v221
	v_add_f32_e32 v221, v103, v221
	v_add_f32_e32 v221, v104, v221
	v_add_f32_e32 v221, v105, v221
	v_add_f32_e32 v221, v106, v221
	v_add_f32_e32 v221, v107, v221
	v_add_f32_e32 v221, v108, v221
	v_add_f32_e32 v221, v109, v221
	v_add_f32_e32 v221, v110, v221
	v_add_f32_e32 v221, v111, v221
	v_mul_f32_e32 v32, v216, v32
	v_mul_f32_e32 v33, v216, v33
	v_mul_f32_e32 v34, v216, v34
	v_mul_f32_e32 v35, v216, v35
	v_mul_f32_e32 v36, v216, v36
	v_mul_f32_e32 v37, v216, v37
	v_mul_f32_e32 v38, v216, v38
	v_mul_f32_e32 v39, v216, v39
	v_mul_f32_e32 v40, v216, v40
	v_mul_f32_e32 v41, v216, v41
	v_mul_f32_e32 v42, v216, v42
	v_mul_f32_e32 v43, v216, v43
	v_mul_f32_e32 v44, v216, v44
	v_mul_f32_e32 v45, v216, v45
	v_mul_f32_e32 v46, v216, v46
	v_mul_f32_e32 v47, v216, v47
	v_fma_f32 v185, v185, v216, v221
	v_cvt_pk_bf16_f32 v152, v96, v97
	v_cvt_pk_bf16_f32 v153, v98, v99
	v_cvt_pk_bf16_f32 v154, v100, v101
	v_cvt_pk_bf16_f32 v155, v102, v103
	v_cvt_pk_bf16_f32 v156, v104, v105
	v_cvt_pk_bf16_f32 v157, v106, v107
	v_cvt_pk_bf16_f32 v158, v108, v109
	v_cvt_pk_bf16_f32 v159, v110, v111
	ds_read_b64 v[128:129], v231 offset:4096
	ds_read_b64 v[130:131], v233 offset:4096
	ds_read_b64 v[132:133], v232 offset:4096
	ds_read_b64 v[134:135], v234 offset:4096
	ds_read_b64 v[136:137], v231 offset:6144
	ds_read_b64 v[138:139], v233 offset:6144
	ds_read_b64 v[140:141], v232 offset:6144
	ds_read_b64 v[142:143], v234 offset:6144
	s_waitcnt lgkmcnt(8)
	v_mfma_f32_16x16x32_bf16 v[16:19], v[112:115], v[144:147], v[16:19]
	v_mfma_f32_16x16x32_bf16 v[32:35], v[112:115], v[152:155], v[32:35]
	v_mfma_f32_16x16x32_bf16 v[16:19], v[116:119], v[148:151], v[16:19]
	v_mfma_f32_16x16x32_bf16 v[32:35], v[116:119], v[156:159], v[32:35]
	v_mfma_f32_16x16x32_bf16 v[20:23], v[120:123], v[144:147], v[20:23]
	v_mfma_f32_16x16x32_bf16 v[36:39], v[120:123], v[152:155], v[36:39]
	v_mfma_f32_16x16x32_bf16 v[20:23], v[124:127], v[148:151], v[20:23]
	v_mfma_f32_16x16x32_bf16 v[36:39], v[124:127], v[156:159], v[36:39]
	s_waitcnt lgkmcnt(0)
	v_mfma_f32_16x16x32_bf16 v[24:27], v[128:131], v[144:147], v[24:27]
	v_mfma_f32_16x16x32_bf16 v[40:43], v[128:131], v[152:155], v[40:43]
	v_mfma_f32_16x16x32_bf16 v[24:27], v[132:135], v[148:151], v[24:27]
	v_mfma_f32_16x16x32_bf16 v[40:43], v[132:135], v[156:159], v[40:43]
	v_mfma_f32_16x16x32_bf16 v[28:31], v[136:139], v[144:147], v[28:31]
	v_mfma_f32_16x16x32_bf16 v[44:47], v[136:139], v[152:155], v[44:47]
	v_mfma_f32_16x16x32_bf16 v[28:31], v[140:143], v[148:151], v[28:31]
	v_mfma_f32_16x16x32_bf16 v[44:47], v[140:143], v[156:159], v[44:47]
	s_branch .Lp4_sel_next
.Lp4_sel_elem:
	v_lshrrev_b32_e32 v215, s26, v188
	v_and_b32_e32 v215, 1, v215
	v_cmp_eq_u32_e64 s[32:33], 1, v215
	v_mov_b32_e32 v216, -1
	v_lshlrev_b32_e32 v217, 2, v198
	v_cndmask_b32_e64 v207, v216, v186, s[32:33]
	v_sub_u32_e32 v207, v207, v217
	v_lshrrev_b32_e32 v215, s26, v189
	v_and_b32_e32 v215, 1, v215
	v_cmp_eq_u32_e64 s[32:33], 1, v215
	v_mov_b32_e32 v216, -1
	v_lshlrev_b32_e32 v217, 2, v198
	v_cndmask_b32_e64 v208, v216, v187, s[32:33]
	v_sub_u32_e32 v208, v208, v217
	v_add_u32_e32 v227, s46, v235
	v_add_u32_e32 v228, s46, v236
	v_add_u32_e32 v231, s46, v237
	v_add_u32_e32 v233, s46, v239
	v_add_u32_e32 v232, s46, v238
	v_add_u32_e32 v234, s46, v240
	ds_read_b128 v[112:115], v227
	ds_read_b128 v[116:119], v228
	ds_read_b128 v[120:123], v227 offset:2048
	ds_read_b128 v[124:127], v228 offset:2048
	ds_read_b128 v[128:131], v227 offset:4096
	ds_read_b128 v[132:135], v228 offset:4096
	ds_read_b128 v[136:139], v227 offset:6144
	ds_read_b128 v[140:143], v228 offset:6144
	s_waitcnt lgkmcnt(7)
	v_mfma_f32_16x16x32_bf16 v[80:83], v[112:115], v[0:3], 0
	v_mfma_f32_16x16x32_bf16 v[96:99], v[112:115], v[8:11], 0
	s_waitcnt lgkmcnt(6)
	v_mfma_f32_16x16x32_bf16 v[80:83], v[116:119], v[4:7], v[80:83]
	v_mfma_f32_16x16x32_bf16 v[96:99], v[116:119], v[12:15], v[96:99]
	s_waitcnt lgkmcnt(5)
	v_mfma_f32_16x16x32_bf16 v[84:87], v[120:123], v[0:3], 0
	v_mfma_f32_16x16x32_bf16 v[100:103], v[120:123], v[8:11], 0
	s_waitcnt lgkmcnt(4)
	v_mfma_f32_16x16x32_bf16 v[84:87], v[124:127], v[4:7], v[84:87]
	v_mfma_f32_16x16x32_bf16 v[100:103], v[124:127], v[12:15], v[100:103]
	s_waitcnt lgkmcnt(3)
	v_mfma_f32_16x16x32_bf16 v[88:91], v[128:131], v[0:3], 0
	v_mfma_f32_16x16x32_bf16 v[104:107], v[128:131], v[8:11], 0
	s_waitcnt lgkmcnt(2)
	v_mfma_f32_16x16x32_bf16 v[88:91], v[132:135], v[4:7], v[88:91]
	v_mfma_f32_16x16x32_bf16 v[104:107], v[132:135], v[12:15], v[104:107]
	s_waitcnt lgkmcnt(1)
	v_mfma_f32_16x16x32_bf16 v[92:95], v[136:139], v[0:3], 0
	v_mfma_f32_16x16x32_bf16 v[108:111], v[136:139], v[8:11], 0
	s_waitcnt lgkmcnt(0)
; DEVI unsigned pack2(float a, float b) { return (unsigned)f2bf(a) | ((unsigned)f2bf(b) << 16); }
; DEVI float fexp2(float x) { return __builtin_amdgcn_exp2f(x); }
; template <int DH, int NQ, int LDK, class MaskF>
; DEVI void attn_qk(const u16* sK, const bf16x8 (&qf)[NQ][DH / 32], f32x4 (&o)[NQ][DH / 16], float (&m)[NQ], float (&l)[NQ],
;                   float c2, int lane, MaskF valid, bf16x8 (&pb)[NQ][2]) {
;     ...
;   for (int qt = 0; qt < NQ; ++qt) {
;     float mx = -1e30f;
; #pragma unroll
;     for (int kt = 0; kt < 4; ++kt)
; #pragma unroll
;       for (int r = 0; r < 4; ++r) {
;         const bool v = valid(qt, 16 * kt + 4 * quad + r);
;         const float sv = v ? s[qt][kt][r] : -1e30f;
;         s[qt][kt][r] = sv;
;         mx = fmaxf(mx, sv);
;       }
;     mx = fmaxf(mx, __shfl_xor(mx, 16));
;     mx = fmaxf(mx, __shfl_xor(mx, 32));
;     const float mn = fmaxf(m[qt], mx);
;     const float alpha = fexp2((m[qt] - mn) * c2);
;     m[qt] = mn;
;     const float mc = fmaxf(mn, -1e20f) * c2;
;     float ps = 0.f;
; #pragma unroll
;     for (int kt = 0; kt < 4; ++kt)
; #pragma unroll
;       for (int r = 0; r < 4; ++r) {
;         const float pv = fexp2(__builtin_fmaf(s[qt][kt][r], c2, -mc));
;         ps += pv;
;         s[qt][kt][r] = pv;
;       }
;     l[qt] = l[qt] * alpha + ps;
; #pragma unroll
;     for (int dt = 0; dt < DH / 16; ++dt) o[qt][dt] *= alpha;
; #pragma unroll
;     for (int kk = 0; kk < 2; ++kk) {
;       union { bf16x8 v; unsigned u[4]; } cv;
;       cv.u[0] = pack2(s[qt][2 * kk][0], s[qt][2 * kk][1]);
;       cv.u[1] = pack2(s[qt][2 * kk][2], s[qt][2 * kk][3]);
;       cv.u[2] = pack2(s[qt][2 * kk + 1][0], s[qt][2 * kk + 1][1]);
;       cv.u[3] = pack2(s[qt][2 * kk + 1][2], s[qt][2 * kk + 1][3]);
;       pb[qt][kk] = cv.v;
;     }
;   }
	v_mfma_f32_16x16x32_bf16 v[92:95], v[140:143], v[4:7], v[92:95]
	v_mfma_f32_16x16x32_bf16 v[108:111], v[140:143], v[12:15], v[108:111]
	ds_read_b64 v[112:113], v231 offset:0
	ds_read_b64 v[114:115], v233 offset:0
	ds_read_b64 v[116:117], v232 offset:0
	ds_read_b64 v[118:119], v234 offset:0
	ds_read_b64 v[120:121], v231 offset:2048
	ds_read_b64 v[122:123], v233 offset:2048
	ds_read_b64 v[124:125], v232 offset:2048
	ds_read_b64 v[126:127], v234 offset:2048
	s_nop 3
	v_subrev_u32_e32 v222, s30, v207
	v_subrev_u32_e32 v223, 0, v222
	v_cmp_ge_u32_e64 s[32:33], s41, v223
	v_subrev_u32_e32 v224, 1, v222
	v_cmp_ge_u32_e64 s[34:35], s41, v224
	v_subrev_u32_e32 v225, 2, v222
	v_cmp_ge_u32_e64 s[36:37], s41, v225
	v_subrev_u32_e32 v226, 3, v222
	v_cmp_ge_u32_e64 s[38:39], s41, v226
	v_cndmask_b32_e64 v80, v230, v80, s[32:33]
	v_cndmask_b32_e64 v81, v230, v81, s[34:35]
	v_cndmask_b32_e64 v82, v230, v82, s[36:37]
	v_cndmask_b32_e64 v83, v230, v83, s[38:39]
	v_subrev_u32_e32 v223, 16, v222
	v_cmp_ge_u32_e64 s[32:33], s41, v223
	v_subrev_u32_e32 v224, 17, v222
	v_cmp_ge_u32_e64 s[34:35], s41, v224
	v_subrev_u32_e32 v225, 18, v222
	v_cmp_ge_u32_e64 s[36:37], s41, v225
	v_subrev_u32_e32 v226, 19, v222
	v_cmp_ge_u32_e64 s[38:39], s41, v226
	v_cndmask_b32_e64 v84, v230, v84, s[32:33]
	v_cndmask_b32_e64 v85, v230, v85, s[34:35]
	v_cndmask_b32_e64 v86, v230, v86, s[36:37]
	v_cndmask_b32_e64 v87, v230, v87, s[38:39]
	v_subrev_u32_e32 v223, 32, v222
	v_cmp_ge_u32_e64 s[32:33], s41, v223
	v_subrev_u32_e32 v224, 33, v222
	v_cmp_ge_u32_e64 s[34:35], s41, v224
	v_subrev_u32_e32 v225, 34, v222
	v_cmp_ge_u32_e64 s[36:37], s41, v225
	v_subrev_u32_e32 v226, 35, v222
	v_cmp_ge_u32_e64 s[38:39], s41, v226
	v_cndmask_b32_e64 v88, v230, v88, s[32:33]
	v_cndmask_b32_e64 v89, v230, v89, s[34:35]
	v_cndmask_b32_e64 v90, v230, v90, s[36:37]
	v_cndmask_b32_e64 v91, v230, v91, s[38:39]
	v_subrev_u32_e32 v223, 48, v222
	v_cmp_ge_u32_e64 s[32:33], s41, v223
	v_subrev_u32_e32 v224, 49, v222
	v_cmp_ge_u32_e64 s[34:35], s41, v224
	v_subrev_u32_e32 v225, 50, v222
	v_cmp_ge_u32_e64 s[36:37], s41, v225
	v_subrev_u32_e32 v226, 51, v222
	v_cmp_ge_u32_e64 s[38:39], s41, v226
	v_cndmask_b32_e64 v92, v230, v92, s[32:33]
	v_cndmask_b32_e64 v93, v230, v93, s[34:35]
	v_cndmask_b32_e64 v94, v230, v94, s[36:37]
	v_cndmask_b32_e64 v95, v230, v95, s[38:39]
	v_max3_f32 v215, v80, v81, v82
	v_max3_f32 v215, v215, v83, v84
	v_max3_f32 v215, v215, v85, v86
	v_max3_f32 v215, v215, v87, v88
	v_max3_f32 v215, v215, v89, v90
	v_max3_f32 v215, v215, v91, v92
	v_max3_f32 v215, v215, v93, v94
	v_max_f32_e32 v215, v95, v215
	ds_bpermute_b32 v217, v195, v215
	s_waitcnt lgkmcnt(0)
	v_max_f32_e32 v215, v217, v215
	v_mov_b32_e32 v217, v215
	v_mov_b32_e32 v218, v215
	s_nop 1
	v_permlane32_swap_b32_e32 v217, v218
	v_max_f32_e32 v215, v217, v218
	v_max_f32_e32 v219, v182, v215
	v_sub_f32_e32 v216, v182, v219
	v_mul_f32_e32 v216, v200, v216
	v_exp_f32_e32 v216, v216
	v_mov_b32_e32 v182, v219
	v_max_f32_e32 v220, 0xe0ad78ec, v219
	v_mul_f32_e32 v220, 0xbe38aa3b, v220
	v_fma_f32 v80, v80, v200, v220
	v_exp_f32_e32 v80, v80
	v_fma_f32 v81, v81, v200, v220
	v_exp_f32_e32 v81, v81
	v_fma_f32 v82, v82, v200, v220
	v_exp_f32_e32 v82, v82
	v_fma_f32 v83, v83, v200, v220
	v_exp_f32_e32 v83, v83
	v_fma_f32 v84, v84, v200, v220
	v_exp_f32_e32 v84, v84
	v_fma_f32 v85, v85, v200, v220
	v_exp_f32_e32 v85, v85
	v_fma_f32 v86, v86, v200, v220
	v_exp_f32_e32 v86, v86
	v_fma_f32 v87, v87, v200, v220
	v_exp_f32_e32 v87, v87
	v_fma_f32 v88, v88, v200, v220
	v_exp_f32_e32 v88, v88
	v_fma_f32 v89, v89, v200, v220
	v_exp_f32_e32 v89, v89
	v_fma_f32 v90, v90, v200, v220
	v_exp_f32_e32 v90, v90
	v_fma_f32 v91, v91, v200, v220
	v_exp_f32_e32 v91, v91
	v_fma_f32 v92, v92, v200, v220
	v_exp_f32_e32 v92, v92
	v_fma_f32 v93, v93, v200, v220
	v_exp_f32_e32 v93, v93
	v_fma_f32 v94, v94, v200, v220
	v_exp_f32_e32 v94, v94
	v_fma_f32 v95, v95, v200, v220
	v_exp_f32_e32 v95, v95
	s_nop 0
	v_add_f32_e32 v221, v80, v81
	v_add_f32_e32 v221, v82, v221
	v_add_f32_e32 v221, v83, v221
	v_add_f32_e32 v221, v84, v221
	v_add_f32_e32 v221, v85, v221
	v_add_f32_e32 v221, v86, v221
	v_add_f32_e32 v221, v87, v221
	v_add_f32_e32 v221, v88, v221
	v_add_f32_e32 v221, v89, v221
	v_add_f32_e32 v221, v90, v221
	v_add_f32_e32 v221, v91, v221
	v_add_f32_e32 v221, v92, v221
	v_add_f32_e32 v221, v93, v221
	v_add_f32_e32 v221, v94, v221
	v_add_f32_e32 v221, v95, v221
	v_mul_f32_e32 v16, v216, v16
	v_mul_f32_e32 v17, v216, v17
	v_mul_f32_e32 v18, v216, v18
	v_mul_f32_e32 v19, v216, v19
	v_mul_f32_e32 v20, v216, v20
	v_mul_f32_e32 v21, v216, v21
	v_mul_f32_e32 v22, v216, v22
	v_mul_f32_e32 v23, v216, v23
	v_mul_f32_e32 v24, v216, v24
	v_mul_f32_e32 v25, v216, v25
	v_mul_f32_e32 v26, v216, v26
	v_mul_f32_e32 v27, v216, v27
	v_mul_f32_e32 v28, v216, v28
	v_mul_f32_e32 v29, v216, v29
	v_mul_f32_e32 v30, v216, v30
	v_mul_f32_e32 v31, v216, v31
	v_fma_f32 v184, v184, v216, v221
	v_cvt_pk_bf16_f32 v144, v80, v81
	v_cvt_pk_bf16_f32 v145, v82, v83
	v_cvt_pk_bf16_f32 v146, v84, v85
	v_cvt_pk_bf16_f32 v147, v86, v87
	v_cvt_pk_bf16_f32 v148, v88, v89
	v_cvt_pk_bf16_f32 v149, v90, v91
	v_cvt_pk_bf16_f32 v150, v92, v93
	v_cvt_pk_bf16_f32 v151, v94, v95
	v_subrev_u32_e32 v222, s30, v208
	v_subrev_u32_e32 v223, 0, v222
	v_cmp_ge_u32_e64 s[32:33], s41, v223
	v_subrev_u32_e32 v224, 1, v222
	v_cmp_ge_u32_e64 s[34:35], s41, v224
	v_subrev_u32_e32 v225, 2, v222
	v_cmp_ge_u32_e64 s[36:37], s41, v225
	v_subrev_u32_e32 v226, 3, v222
	v_cmp_ge_u32_e64 s[38:39], s41, v226
	v_cndmask_b32_e64 v96, v230, v96, s[32:33]
	v_cndmask_b32_e64 v97, v230, v97, s[34:35]
	v_cndmask_b32_e64 v98, v230, v98, s[36:37]
; template <int DH, int NQ, int LDK, class MaskF>
; DEVI void attn_qk(const u16* sK, const bf16x8 (&qf)[NQ][DH / 32], f32x4 (&o)[NQ][DH / 16], float (&m)[NQ], float (&l)[NQ],
;                   float c2, int lane, MaskF valid, bf16x8 (&pb)[NQ][2]) {
;     ...
;   for (int qt = 0; qt < NQ; ++qt) {
;     float mx = -1e30f;
; #pragma unroll
;     for (int kt = 0; kt < 4; ++kt)
; #pragma unroll
;       for (int r = 0; r < 4; ++r) {
;         const bool v = valid(qt, 16 * kt + 4 * quad + r);
;         const float sv = v ? s[qt][kt][r] : -1e30f;
;         s[qt][kt][r] = sv;
;         mx = fmaxf(mx, sv);
;       }
;     mx = fmaxf(mx, __shfl_xor(mx, 16));
;     mx = fmaxf(mx, __shfl_xor(mx, 32));
;     const float mn = fmaxf(m[qt], mx);
;     const float alpha = fexp2((m[qt] - mn) * c2);
;     m[qt] = mn;
;     const float mc = fmaxf(mn, -1e20f) * c2;
;     float ps = 0.f;
; #pragma unroll
;     for (int kt = 0; kt < 4; ++kt)
; #pragma unroll
;       for (int r = 0; r < 4; ++r) {
;         const float pv = fexp2(__builtin_fmaf(s[qt][kt][r], c2, -mc));
;         ps += pv;
;         s[qt][kt][r] = pv;
;       }
;     l[qt] = l[qt] * alpha + ps;
; #pragma unroll
;     for (int dt = 0; dt < DH / 16; ++dt) o[qt][dt] *= alpha;
; #pragma unroll
;     for (int kk = 0; kk < 2; ++kk) {
;       union { bf16x8 v; unsigned u[4]; } cv;
;       cv.u[0] = pack2(s[qt][2 * kk][0], s[qt][2 * kk][1]);
;       cv.u[1] = pack2(s[qt][2 * kk][2], s[qt][2 * kk][3]);
;       cv.u[2] = pack2(s[qt][2 * kk + 1][0], s[qt][2 * kk + 1][1]);
;       cv.u[3] = pack2(s[qt][2 * kk + 1][2], s[qt][2 * kk + 1][3]);
;       pb[qt][kk] = cv.v;
;     }
;   }
; }
; template <int DH, int NQ, int LDV>
; DEVI void attn_pv(const u16* sVt, const bf16x8 (&pb)[NQ][2], f32x4 (&o)[NQ][DH / 16], int lane) {
;   const int col = lane & 15, quad = lane >> 4;
;   __builtin_amdgcn_s_setprio(1);
; #pragma unroll
;   for (int dt = 0; dt < DH / 16; ++dt) {
; #pragma unroll
;     for (int kk = 0; kk < 2; ++kk) {
;       union { bf16x8 v; uint2 h[2]; } cv;
;       cv.h[0] = *(const uint2*)(sVt + (16 * dt + col) * LDV + 32 * kk + 4 * quad);
;       cv.h[1] = *(const uint2*)(sVt + (16 * dt + col) * LDV + 32 * kk + 16 + 4 * quad);
; #pragma unroll
;       for (int qt = 0; qt < NQ; ++qt) o[qt][dt] = mfma16(cv.v, pb[qt][kk], o[qt][dt]);
;     }
;   }
;   __builtin_amdgcn_s_setprio(0);
	v_cndmask_b32_e64 v99, v230, v99, s[38:39]
	v_subrev_u32_e32 v223, 16, v222
	v_cmp_ge_u32_e64 s[32:33], s41, v223
	v_subrev_u32_e32 v224, 17, v222
	v_cmp_ge_u32_e64 s[34:35], s41, v224
	v_subrev_u32_e32 v225, 18, v222
	v_cmp_ge_u32_e64 s[36:37], s41, v225
	v_subrev_u32_e32 v226, 19, v222
	v_cmp_ge_u32_e64 s[38:39], s41, v226
	v_cndmask_b32_e64 v100, v230, v100, s[32:33]
	v_cndmask_b32_e64 v101, v230, v101, s[34:35]
	v_cndmask_b32_e64 v102, v230, v102, s[36:37]
	v_cndmask_b32_e64 v103, v230, v103, s[38:39]
	v_subrev_u32_e32 v223, 32, v222
	v_cmp_ge_u32_e64 s[32:33], s41, v223
	v_subrev_u32_e32 v224, 33, v222
	v_cmp_ge_u32_e64 s[34:35], s41, v224
	v_subrev_u32_e32 v225, 34, v222
	v_cmp_ge_u32_e64 s[36:37], s41, v225
	v_subrev_u32_e32 v226, 35, v222
	v_cmp_ge_u32_e64 s[38:39], s41, v226
	v_cndmask_b32_e64 v104, v230, v104, s[32:33]
	v_cndmask_b32_e64 v105, v230, v105, s[34:35]
	v_cndmask_b32_e64 v106, v230, v106, s[36:37]
	v_cndmask_b32_e64 v107, v230, v107, s[38:39]
	v_subrev_u32_e32 v223, 48, v222
	v_cmp_ge_u32_e64 s[32:33], s41, v223
	v_subrev_u32_e32 v224, 49, v222
	v_cmp_ge_u32_e64 s[34:35], s41, v224
	v_subrev_u32_e32 v225, 50, v222
	v_cmp_ge_u32_e64 s[36:37], s41, v225
	v_subrev_u32_e32 v226, 51, v222
	v_cmp_ge_u32_e64 s[38:39], s41, v226
	v_cndmask_b32_e64 v108, v230, v108, s[32:33]
	v_cndmask_b32_e64 v109, v230, v109, s[34:35]
	v_cndmask_b32_e64 v110, v230, v110, s[36:37]
	v_cndmask_b32_e64 v111, v230, v111, s[38:39]
	v_max3_f32 v215, v96, v97, v98
	v_max3_f32 v215, v215, v99, v100
	v_max3_f32 v215, v215, v101, v102
	v_max3_f32 v215, v215, v103, v104
	v_max3_f32 v215, v215, v105, v106
	v_max3_f32 v215, v215, v107, v108
	v_max3_f32 v215, v215, v109, v110
	v_max_f32_e32 v215, v111, v215
	ds_bpermute_b32 v217, v195, v215
	s_waitcnt lgkmcnt(0)
	v_max_f32_e32 v215, v217, v215
	v_mov_b32_e32 v217, v215
	v_mov_b32_e32 v218, v215
	s_nop 1
	v_permlane32_swap_b32_e32 v217, v218
	v_max_f32_e32 v215, v217, v218
	v_max_f32_e32 v219, v183, v215
	v_sub_f32_e32 v216, v183, v219
	v_mul_f32_e32 v216, v200, v216
	v_exp_f32_e32 v216, v216
	v_mov_b32_e32 v183, v219
	v_max_f32_e32 v220, 0xe0ad78ec, v219
	v_mul_f32_e32 v220, 0xbe38aa3b, v220
	v_fma_f32 v96, v96, v200, v220
	v_exp_f32_e32 v96, v96
	v_fma_f32 v97, v97, v200, v220
	v_exp_f32_e32 v97, v97
	v_fma_f32 v98, v98, v200, v220
	v_exp_f32_e32 v98, v98
	v_fma_f32 v99, v99, v200, v220
	v_exp_f32_e32 v99, v99
	v_fma_f32 v100, v100, v200, v220
	v_exp_f32_e32 v100, v100
	v_fma_f32 v101, v101, v200, v220
	v_exp_f32_e32 v101, v101
	v_fma_f32 v102, v102, v200, v220
	v_exp_f32_e32 v102, v102
	v_fma_f32 v103, v103, v200, v220
	v_exp_f32_e32 v103, v103
	v_fma_f32 v104, v104, v200, v220
	v_exp_f32_e32 v104, v104
	v_fma_f32 v105, v105, v200, v220
	v_exp_f32_e32 v105, v105
	v_fma_f32 v106, v106, v200, v220
	v_exp_f32_e32 v106, v106
	v_fma_f32 v107, v107, v200, v220
	v_exp_f32_e32 v107, v107
	v_fma_f32 v108, v108, v200, v220
	v_exp_f32_e32 v108, v108
	v_fma_f32 v109, v109, v200, v220
	v_exp_f32_e32 v109, v109
	v_fma_f32 v110, v110, v200, v220
	v_exp_f32_e32 v110, v110
	v_fma_f32 v111, v111, v200, v220
	v_exp_f32_e32 v111, v111
	s_nop 0
	v_add_f32_e32 v221, v96, v97
	v_add_f32_e32 v221, v98, v221
	v_add_f32_e32 v221, v99, v221
	v_add_f32_e32 v221, v100, v221
	v_add_f32_e32 v221, v101, v221
	v_add_f32_e32 v221, v102, v221
	v_add_f32_e32 v221, v103, v221
	v_add_f32_e32 v221, v104, v221
	v_add_f32_e32 v221, v105, v221
	v_add_f32_e32 v221, v106, v221
	v_add_f32_e32 v221, v107, v221
	v_add_f32_e32 v221, v108, v221
	v_add_f32_e32 v221, v109, v221
	v_add_f32_e32 v221, v110, v221
	v_add_f32_e32 v221, v111, v221
	v_mul_f32_e32 v32, v216, v32
	v_mul_f32_e32 v33, v216, v33
	v_mul_f32_e32 v34, v216, v34
	v_mul_f32_e32 v35, v216, v35
	v_mul_f32_e32 v36, v216, v36
	v_mul_f32_e32 v37, v216, v37
	v_mul_f32_e32 v38, v216, v38
	v_mul_f32_e32 v39, v216, v39
	v_mul_f32_e32 v40, v216, v40
	v_mul_f32_e32 v41, v216, v41
	v_mul_f32_e32 v42, v216, v42
	v_mul_f32_e32 v43, v216, v43
	v_mul_f32_e32 v44, v216, v44
	v_mul_f32_e32 v45, v216, v45
	v_mul_f32_e32 v46, v216, v46
	v_mul_f32_e32 v47, v216, v47
	v_fma_f32 v185, v185, v216, v221
	v_cvt_pk_bf16_f32 v152, v96, v97
	v_cvt_pk_bf16_f32 v153, v98, v99
	v_cvt_pk_bf16_f32 v154, v100, v101
	v_cvt_pk_bf16_f32 v155, v102, v103
	v_cvt_pk_bf16_f32 v156, v104, v105
	v_cvt_pk_bf16_f32 v157, v106, v107
	v_cvt_pk_bf16_f32 v158, v108, v109
	v_cvt_pk_bf16_f32 v159, v110, v111
	ds_read_b64 v[128:129], v231 offset:4096
	ds_read_b64 v[130:131], v233 offset:4096
	ds_read_b64 v[132:133], v232 offset:4096
	ds_read_b64 v[134:135], v234 offset:4096
	ds_read_b64 v[136:137], v231 offset:6144
	ds_read_b64 v[138:139], v233 offset:6144
	ds_read_b64 v[140:141], v232 offset:6144
	ds_read_b64 v[142:143], v234 offset:6144
	s_waitcnt lgkmcnt(8)
	v_mfma_f32_16x16x32_bf16 v[16:19], v[112:115], v[144:147], v[16:19]
	v_mfma_f32_16x16x32_bf16 v[32:35], v[112:115], v[152:155], v[32:35]
	v_mfma_f32_16x16x32_bf16 v[16:19], v[116:119], v[148:151], v[16:19]
	v_mfma_f32_16x16x32_bf16 v[32:35], v[116:119], v[156:159], v[32:35]
	v_mfma_f32_16x16x32_bf16 v[20:23], v[120:123], v[144:147], v[20:23]
	v_mfma_f32_16x16x32_bf16 v[36:39], v[120:123], v[152:155], v[36:39]
	v_mfma_f32_16x16x32_bf16 v[20:23], v[124:127], v[148:151], v[20:23]
	v_mfma_f32_16x16x32_bf16 v[36:39], v[124:127], v[156:159], v[36:39]
	s_waitcnt lgkmcnt(0)
	v_mfma_f32_16x16x32_bf16 v[24:27], v[128:131], v[144:147], v[24:27]
	v_mfma_f32_16x16x32_bf16 v[40:43], v[128:131], v[152:155], v[40:43]
	v_mfma_f32_16x16x32_bf16 v[24:27], v[132:135], v[148:151], v[24:27]
	v_mfma_f32_16x16x32_bf16 v[40:43], v[132:135], v[156:159], v[40:43]
	v_mfma_f32_16x16x32_bf16 v[28:31], v[136:139], v[144:147], v[28:31]
	v_mfma_f32_16x16x32_bf16 v[44:47], v[136:139], v[152:155], v[44:47]
	v_mfma_f32_16x16x32_bf16 v[28:31], v[140:143], v[148:151], v[28:31]
	v_mfma_f32_16x16x32_bf16 v[44:47], v[140:143], v[156:159], v[44:47]

; DEVI f32x4 mfma16(bf16x8 a, bf16x8 b, f32x4 c) { return __builtin_amdgcn_mfma_f32_16x16x32_bf16(a, b, c, 0, 0, 0); }
; DEVI float fexp2(float x) { return __builtin_amdgcn_exp2f(x); }
; template <int DH, int NQ, int LDK, class MaskF>
; DEVI void attn_qk(const u16* sK, const bf16x8 (&qf)[NQ][DH / 32], f32x4 (&o)[NQ][DH / 16], float (&m)[NQ], float (&l)[NQ],
;                   float c2, int lane, MaskF valid, bf16x8 (&pb)[NQ][2]) {
;   const int col = lane & 15, quad = lane >> 4;
;   f32x4 s[NQ][4];
;   __builtin_amdgcn_s_setprio(1);
; #pragma unroll
;   for (int kt = 0; kt < 4; ++kt) {
; #pragma unroll
;     for (int qt = 0; qt < NQ; ++qt) s[qt][kt] = f32x4{0.f, 0.f, 0.f, 0.f};
; #pragma unroll
;     for (int ks = 0; ks < DH / 32; ++ks) {
;       const bf16x8 kf = *(const bf16x8*)(sK + (16 * kt + col) * LDK + 32 * ks + 8 * quad);
; #pragma unroll
;       for (int qt = 0; qt < NQ; ++qt) s[qt][kt] = mfma16(kf, qf[qt][ks], s[qt][kt]);
;     }
;   }
;   __builtin_amdgcn_s_setprio(0);
; #pragma unroll
;   for (int qt = 0; qt < NQ; ++qt) {
;     float mx = -1e30f;
; #pragma unroll
;     for (int kt = 0; kt < 4; ++kt)
; #pragma unroll
;       for (int r = 0; r < 4; ++r) {
;         const bool v = valid(qt, 16 * kt + 4 * quad + r);
;         const float sv = v ? s[qt][kt][r] : -1e30f;
;         s[qt][kt][r] = sv;
;         mx = fmaxf(mx, sv);
;       }
;     mx = fmaxf(mx, __shfl_xor(mx, 16));
;     mx = fmaxf(mx, __shfl_xor(mx, 32));
;     const float mn = fmaxf(m[qt], mx);
;     const float alpha = fexp2((m[qt] - mn) * c2);
; DEVI void phase_nsa(const Params& p, unsigned char* smem) {
;     ...
;       while (kb >= 0) {
;         const int nkb = (kb < kbmax) ? kb + 1 : -1;
;         __syncthreads();
;         STOREKV_()
;         if (nkb >= 0) { LOADKV_(nkb, C_KW, p.vtw) }
;         __syncthreads();
;         attn_tile<64, 2, 72, 72>(sK, sVt, qf, o, m, l, c2, lane, [&](int qt, int kl) {
;           return (unsigned)(tq[qt] - (kb * 64 + kl)) < 512u;
;         });
.Lp4_win_nq3:
	s_lshl_b32 s30, s26, 6
	s_add_u32 s23, s30, 63
	s_cmp_le_u32 s23, s19
	s_cselect_b32 s24, 1, 0
	s_add_u32 s23, s30, 0x1e0
	s_cmp_ge_u32 s23, s19
	s_cselect_b32 s24, s24, 0
	s_cmp_eq_u32 s24, 0
	s_cbranch_scc1 .Lp4_win_masked
	v_add_u32_e32 v227, s46, v235
	v_add_u32_e32 v228, s46, v236
	v_add_u32_e32 v231, s46, v237
	v_add_u32_e32 v233, s46, v239
	v_add_u32_e32 v232, s46, v238
	v_add_u32_e32 v234, s46, v240
	ds_read_b128 v[112:115], v227
	ds_read_b128 v[116:119], v228
	ds_read_b128 v[120:123], v227 offset:2048
	ds_read_b128 v[124:127], v228 offset:2048
	ds_read_b128 v[128:131], v227 offset:4096
	ds_read_b128 v[132:135], v228 offset:4096
	ds_read_b128 v[136:139], v227 offset:6144
	ds_read_b128 v[140:143], v228 offset:6144
	s_waitcnt lgkmcnt(7)
	v_mfma_f32_16x16x32_bf16 v[80:83], v[112:115], v[0:3], 0
	v_mfma_f32_16x16x32_bf16 v[96:99], v[112:115], v[8:11], 0
	s_waitcnt lgkmcnt(6)
	v_mfma_f32_16x16x32_bf16 v[80:83], v[116:119], v[4:7], v[80:83]
	v_mfma_f32_16x16x32_bf16 v[96:99], v[116:119], v[12:15], v[96:99]
	s_waitcnt lgkmcnt(5)
	v_mfma_f32_16x16x32_bf16 v[84:87], v[120:123], v[0:3], 0
	v_mfma_f32_16x16x32_bf16 v[100:103], v[120:123], v[8:11], 0
	s_waitcnt lgkmcnt(4)
	v_mfma_f32_16x16x32_bf16 v[84:87], v[124:127], v[4:7], v[84:87]
	v_mfma_f32_16x16x32_bf16 v[100:103], v[124:127], v[12:15], v[100:103]
	s_waitcnt lgkmcnt(3)
	v_mfma_f32_16x16x32_bf16 v[88:91], v[128:131], v[0:3], 0
	v_mfma_f32_16x16x32_bf16 v[104:107], v[128:131], v[8:11], 0
	s_waitcnt lgkmcnt(2)
	v_mfma_f32_16x16x32_bf16 v[88:91], v[132:135], v[4:7], v[88:91]
	v_mfma_f32_16x16x32_bf16 v[104:107], v[132:135], v[12:15], v[104:107]
	s_waitcnt lgkmcnt(1)
	v_mfma_f32_16x16x32_bf16 v[92:95], v[136:139], v[0:3], 0
	v_mfma_f32_16x16x32_bf16 v[108:111], v[136:139], v[8:11], 0
	s_waitcnt lgkmcnt(0)
	v_mfma_f32_16x16x32_bf16 v[92:95], v[140:143], v[4:7], v[92:95]
	v_mfma_f32_16x16x32_bf16 v[108:111], v[140:143], v[12:15], v[108:111]
	ds_read_b64 v[112:113], v231 offset:0
	ds_read_b64 v[114:115], v233 offset:0
	ds_read_b64 v[116:117], v232 offset:0
	ds_read_b64 v[118:119], v234 offset:0
	ds_read_b64 v[120:121], v231 offset:2048
	ds_read_b64 v[122:123], v233 offset:2048
	ds_read_b64 v[124:125], v232 offset:2048
	ds_read_b64 v[126:127], v234 offset:2048
	s_nop 3
	v_max3_f32 v215, v80, v81, v82
	v_max3_f32 v215, v215, v83, v84
	v_max3_f32 v215, v215, v85, v86
	v_max3_f32 v215, v215, v87, v88
	v_max3_f32 v215, v215, v89, v90
	v_max3_f32 v215, v215, v91, v92
	v_max3_f32 v215, v215, v93, v94
	v_max_f32_e32 v215, v95, v215
	ds_bpermute_b32 v217, v195, v215
	s_waitcnt lgkmcnt(0)
	v_max_f32_e32 v215, v217, v215
	v_mov_b32_e32 v217, v215
	v_mov_b32_e32 v218, v215
	s_nop 1
	v_permlane32_swap_b32_e32 v217, v218
	v_max_f32_e32 v215, v217, v218
	v_max_f32_e32 v219, v182, v215
	v_sub_f32_e32 v216, v182, v219
	v_mul_f32_e32 v216, v200, v216
	v_exp_f32_e32 v216, v216
	v_mov_b32_e32 v182, v219
	v_max_f32_e32 v220, 0xe0ad78ec, v219
	v_mul_f32_e32 v220, 0xbe38aa3b, v220
	v_fma_f32 v80, v80, v200, v220
	v_exp_f32_e32 v80, v80
	v_fma_f32 v81, v81, v200, v220
	v_exp_f32_e32 v81, v81
	v_fma_f32 v82, v82, v200, v220
	v_exp_f32_e32 v82, v82
	v_fma_f32 v83, v83, v200, v220
	v_exp_f32_e32 v83, v83
	v_fma_f32 v84, v84, v200, v220
	v_exp_f32_e32 v84, v84
	v_fma_f32 v85, v85, v200, v220
	v_exp_f32_e32 v85, v85
	v_fma_f32 v86, v86, v200, v220
	v_exp_f32_e32 v86, v86
	v_fma_f32 v87, v87, v200, v220
	v_exp_f32_e32 v87, v87
	v_fma_f32 v88, v88, v200, v220
	v_exp_f32_e32 v88, v88
	v_fma_f32 v89, v89, v200, v220
	v_exp_f32_e32 v89, v89
	v_fma_f32 v90, v90, v200, v220
	v_exp_f32_e32 v90, v90
	v_fma_f32 v91, v91, v200, v220
	v_exp_f32_e32 v91, v91
	v_fma_f32 v92, v92, v200, v220
	v_exp_f32_e32 v92, v92
	v_fma_f32 v93, v93, v200, v220
	v_exp_f32_e32 v93, v93
	v_fma_f32 v94, v94, v200, v220
	v_exp_f32_e32 v94, v94
	v_fma_f32 v95, v95, v200, v220
	v_exp_f32_e32 v95, v95
	s_nop 0
	v_add_f32_e32 v221, v80, v81
	v_add_f32_e32 v221, v82, v221
	v_add_f32_e32 v221, v83, v221
	v_add_f32_e32 v221, v84, v221
	v_add_f32_e32 v221, v85, v221
	v_add_f32_e32 v221, v86, v221
	v_add_f32_e32 v221, v87, v221
	v_add_f32_e32 v221, v88, v221
	v_add_f32_e32 v221, v89, v221
	v_add_f32_e32 v221, v90, v221
	v_add_f32_e32 v221, v91, v221
	v_add_f32_e32 v221, v92, v221
	v_add_f32_e32 v221, v93, v221
	v_add_f32_e32 v221, v94, v221
	v_add_f32_e32 v221, v95, v221
	v_mul_f32_e32 v16, v216, v16
	v_mul_f32_e32 v17, v216, v17
	v_mul_f32_e32 v18, v216, v18
	v_mul_f32_e32 v19, v216, v19
	v_mul_f32_e32 v20, v216, v20
	v_mul_f32_e32 v21, v216, v21
	v_mul_f32_e32 v22, v216, v22
	v_mul_f32_e32 v23, v216, v23
	v_mul_f32_e32 v24, v216, v24
	v_mul_f32_e32 v25, v216, v25
	v_mul_f32_e32 v26, v216, v26
	v_mul_f32_e32 v27, v216, v27
	v_mul_f32_e32 v28, v216, v28
	v_mul_f32_e32 v29, v216, v29
	v_mul_f32_e32 v30, v216, v30
	v_mul_f32_e32 v31, v216, v31
	v_fma_f32 v184, v184, v216, v221
	v_cvt_pk_bf16_f32 v144, v80, v81
	v_cvt_pk_bf16_f32 v145, v82, v83
	v_cvt_pk_bf16_f32 v146, v84, v85
	v_cvt_pk_bf16_f32 v147, v86, v87
	v_cvt_pk_bf16_f32 v148, v88, v89
	v_cvt_pk_bf16_f32 v149, v90, v91
	v_cvt_pk_bf16_f32 v150, v92, v93
	v_cvt_pk_bf16_f32 v151, v94, v95
	v_max3_f32 v215, v96, v97, v98
	v_max3_f32 v215, v215, v99, v100
	v_max3_f32 v215, v215, v101, v102
	v_max3_f32 v215, v215, v103, v104
	v_max3_f32 v215, v215, v105, v106
	v_max3_f32 v215, v215, v107, v108
	v_max3_f32 v215, v215, v109, v110
	v_max_f32_e32 v215, v111, v215
	ds_bpermute_b32 v217, v195, v215
	s_waitcnt lgkmcnt(0)
; DEVI unsigned pack2(float a, float b) { return (unsigned)f2bf(a) | ((unsigned)f2bf(b) << 16); }
; DEVI f32x4 mfma16(bf16x8 a, bf16x8 b, f32x4 c) { return __builtin_amdgcn_mfma_f32_16x16x32_bf16(a, b, c, 0, 0, 0); }
; DEVI float fexp2(float x) { return __builtin_amdgcn_exp2f(x); }
; template <int DH, int NQ, int LDK, class MaskF>
; DEVI void attn_qk(const u16* sK, const bf16x8 (&qf)[NQ][DH / 32], f32x4 (&o)[NQ][DH / 16], float (&m)[NQ], float (&l)[NQ],
;                   float c2, int lane, MaskF valid, bf16x8 (&pb)[NQ][2]) {
;     ...
;     mx = fmaxf(mx, __shfl_xor(mx, 16));
;     mx = fmaxf(mx, __shfl_xor(mx, 32));
;     const float mn = fmaxf(m[qt], mx);
;     const float alpha = fexp2((m[qt] - mn) * c2);
;     m[qt] = mn;
;     const float mc = fmaxf(mn, -1e20f) * c2;
;     float ps = 0.f;
; #pragma unroll
;     for (int kt = 0; kt < 4; ++kt)
; #pragma unroll
;       for (int r = 0; r < 4; ++r) {
;         const float pv = fexp2(__builtin_fmaf(s[qt][kt][r], c2, -mc));
;         ps += pv;
;         s[qt][kt][r] = pv;
;       }
;     l[qt] = l[qt] * alpha + ps;
; #pragma unroll
;     for (int dt = 0; dt < DH / 16; ++dt) o[qt][dt] *= alpha;
; #pragma unroll
;     for (int kk = 0; kk < 2; ++kk) {
;       union { bf16x8 v; unsigned u[4]; } cv;
;       cv.u[0] = pack2(s[qt][2 * kk][0], s[qt][2 * kk][1]);
;       cv.u[1] = pack2(s[qt][2 * kk][2], s[qt][2 * kk][3]);
;       cv.u[2] = pack2(s[qt][2 * kk + 1][0], s[qt][2 * kk + 1][1]);
;       cv.u[3] = pack2(s[qt][2 * kk + 1][2], s[qt][2 * kk + 1][3]);
;       pb[qt][kk] = cv.v;
;     }
;   }
; }
; template <int DH, int NQ, int LDV>
; DEVI void attn_pv(const u16* sVt, const bf16x8 (&pb)[NQ][2], f32x4 (&o)[NQ][DH / 16], int lane) {
;   const int col = lane & 15, quad = lane >> 4;
;   __builtin_amdgcn_s_setprio(1);
; #pragma unroll
;   for (int dt = 0; dt < DH / 16; ++dt) {
; #pragma unroll
;     for (int kk = 0; kk < 2; ++kk) {
;       union { bf16x8 v; uint2 h[2]; } cv;
;       cv.h[0] = *(const uint2*)(sVt + (16 * dt + col) * LDV + 32 * kk + 4 * quad);
;       cv.h[1] = *(const uint2*)(sVt + (16 * dt + col) * LDV + 32 * kk + 16 + 4 * quad);
; #pragma unroll
;       for (int qt = 0; qt < NQ; ++qt) o[qt][dt] = mfma16(cv.v, pb[qt][kk], o[qt][dt]);
;     }
;   }
;   __builtin_amdgcn_s_setprio(0);
	v_max_f32_e32 v215, v217, v215
	v_mov_b32_e32 v217, v215
	v_mov_b32_e32 v218, v215
	s_nop 1
	v_permlane32_swap_b32_e32 v217, v218
	v_max_f32_e32 v215, v217, v218
	v_max_f32_e32 v219, v183, v215
	v_sub_f32_e32 v216, v183, v219
	v_mul_f32_e32 v216, v200, v216
	v_exp_f32_e32 v216, v216
	v_mov_b32_e32 v183, v219
	v_max_f32_e32 v220, 0xe0ad78ec, v219
	v_mul_f32_e32 v220, 0xbe38aa3b, v220
	v_fma_f32 v96, v96, v200, v220
	v_exp_f32_e32 v96, v96
	v_fma_f32 v97, v97, v200, v220
	v_exp_f32_e32 v97, v97
	v_fma_f32 v98, v98, v200, v220
	v_exp_f32_e32 v98, v98
	v_fma_f32 v99, v99, v200, v220
	v_exp_f32_e32 v99, v99
	v_fma_f32 v100, v100, v200, v220
	v_exp_f32_e32 v100, v100
	v_fma_f32 v101, v101, v200, v220
	v_exp_f32_e32 v101, v101
	v_fma_f32 v102, v102, v200, v220
	v_exp_f32_e32 v102, v102
	v_fma_f32 v103, v103, v200, v220
	v_exp_f32_e32 v103, v103
	v_fma_f32 v104, v104, v200, v220
	v_exp_f32_e32 v104, v104
	v_fma_f32 v105, v105, v200, v220
	v_exp_f32_e32 v105, v105
	v_fma_f32 v106, v106, v200, v220
	v_exp_f32_e32 v106, v106
	v_fma_f32 v107, v107, v200, v220
	v_exp_f32_e32 v107, v107
	v_fma_f32 v108, v108, v200, v220
	v_exp_f32_e32 v108, v108
	v_fma_f32 v109, v109, v200, v220
	v_exp_f32_e32 v109, v109
	v_fma_f32 v110, v110, v200, v220
	v_exp_f32_e32 v110, v110
	v_fma_f32 v111, v111, v200, v220
	v_exp_f32_e32 v111, v111
	s_nop 0
	v_add_f32_e32 v221, v96, v97
	v_add_f32_e32 v221, v98, v221
	v_add_f32_e32 v221, v99, v221
	v_add_f32_e32 v221, v100, v221
	v_add_f32_e32 v221, v101, v221
	v_add_f32_e32 v221, v102, v221
	v_add_f32_e32 v221, v103, v221
	v_add_f32_e32 v221, v104, v221
	v_add_f32_e32 v221, v105, v221
	v_add_f32_e32 v221, v106, v221
	v_add_f32_e32 v221, v107, v221
	v_add_f32_e32 v221, v108, v221
	v_add_f32_e32 v221, v109, v221
	v_add_f32_e32 v221, v110, v221
	v_add_f32_e32 v221, v111, v221
	v_mul_f32_e32 v32, v216, v32
	v_mul_f32_e32 v33, v216, v33
	v_mul_f32_e32 v34, v216, v34
	v_mul_f32_e32 v35, v216, v35
	v_mul_f32_e32 v36, v216, v36
	v_mul_f32_e32 v37, v216, v37
	v_mul_f32_e32 v38, v216, v38
	v_mul_f32_e32 v39, v216, v39
	v_mul_f32_e32 v40, v216, v40
	v_mul_f32_e32 v41, v216, v41
	v_mul_f32_e32 v42, v216, v42
	v_mul_f32_e32 v43, v216, v43
	v_mul_f32_e32 v44, v216, v44
	v_mul_f32_e32 v45, v216, v45
	v_mul_f32_e32 v46, v216, v46
	v_mul_f32_e32 v47, v216, v47
	v_fma_f32 v185, v185, v216, v221
	v_cvt_pk_bf16_f32 v152, v96, v97
	v_cvt_pk_bf16_f32 v153, v98, v99
	v_cvt_pk_bf16_f32 v154, v100, v101
	v_cvt_pk_bf16_f32 v155, v102, v103
	v_cvt_pk_bf16_f32 v156, v104, v105
	v_cvt_pk_bf16_f32 v157, v106, v107
	v_cvt_pk_bf16_f32 v158, v108, v109
	v_cvt_pk_bf16_f32 v159, v110, v111
	ds_read_b64 v[128:129], v231 offset:4096
	ds_read_b64 v[130:131], v233 offset:4096
	ds_read_b64 v[132:133], v232 offset:4096
	ds_read_b64 v[134:135], v234 offset:4096
	ds_read_b64 v[136:137], v231 offset:6144
	ds_read_b64 v[138:139], v233 offset:6144
	ds_read_b64 v[140:141], v232 offset:6144
	ds_read_b64 v[142:143], v234 offset:6144
	s_waitcnt lgkmcnt(8)
	v_mfma_f32_16x16x32_bf16 v[16:19], v[112:115], v[144:147], v[16:19]
	v_mfma_f32_16x16x32_bf16 v[32:35], v[112:115], v[152:155], v[32:35]
	v_mfma_f32_16x16x32_bf16 v[16:19], v[116:119], v[148:151], v[16:19]
	v_mfma_f32_16x16x32_bf16 v[32:35], v[116:119], v[156:159], v[32:35]
	v_mfma_f32_16x16x32_bf16 v[20:23], v[120:123], v[144:147], v[20:23]
	v_mfma_f32_16x16x32_bf16 v[36:39], v[120:123], v[152:155], v[36:39]
	v_mfma_f32_16x16x32_bf16 v[20:23], v[124:127], v[148:151], v[20:23]
	v_mfma_f32_16x16x32_bf16 v[36:39], v[124:127], v[156:159], v[36:39]
	s_waitcnt lgkmcnt(0)
	v_mfma_f32_16x16x32_bf16 v[24:27], v[128:131], v[144:147], v[24:27]
	v_mfma_f32_16x16x32_bf16 v[40:43], v[128:131], v[152:155], v[40:43]
	v_mfma_f32_16x16x32_bf16 v[24:27], v[132:135], v[148:151], v[24:27]
	v_mfma_f32_16x16x32_bf16 v[40:43], v[132:135], v[156:159], v[40:43]
	v_mfma_f32_16x16x32_bf16 v[28:31], v[136:139], v[144:147], v[28:31]
	v_mfma_f32_16x16x32_bf16 v[44:47], v[136:139], v[152:155], v[44:47]
	v_mfma_f32_16x16x32_bf16 v[28:31], v[140:143], v[148:151], v[28:31]
	v_mfma_f32_16x16x32_bf16 v[44:47], v[140:143], v[156:159], v[44:47]
	s_branch .Lp4_win_next
.Lp4_win_masked:
	v_lshlrev_b32_e32 v217, 2, v198
	v_sub_u32_e32 v207, v186, v217
	v_lshlrev_b32_e32 v217, 2, v198
	v_sub_u32_e32 v208, v187, v217
	v_add_u32_e32 v227, s46, v235
	v_add_u32_e32 v228, s46, v236
	v_add_u32_e32 v231, s46, v237
	v_add_u32_e32 v233, s46, v239
	v_add_u32_e32 v232, s46, v238
	v_add_u32_e32 v234, s46, v240
	ds_read_b128 v[112:115], v227
	ds_read_b128 v[116:119], v228
	ds_read_b128 v[120:123], v227 offset:2048
	ds_read_b128 v[124:127], v228 offset:2048
	ds_read_b128 v[128:131], v227 offset:4096
	ds_read_b128 v[132:135], v228 offset:4096
	ds_read_b128 v[136:139], v227 offset:6144
	ds_read_b128 v[140:143], v228 offset:6144
	s_waitcnt lgkmcnt(7)
	v_mfma_f32_16x16x32_bf16 v[80:83], v[112:115], v[0:3], 0
	v_mfma_f32_16x16x32_bf16 v[96:99], v[112:115], v[8:11], 0
	s_waitcnt lgkmcnt(6)
	v_mfma_f32_16x16x32_bf16 v[80:83], v[116:119], v[4:7], v[80:83]
	v_mfma_f32_16x16x32_bf16 v[96:99], v[116:119], v[12:15], v[96:99]
	s_waitcnt lgkmcnt(5)
	v_mfma_f32_16x16x32_bf16 v[84:87], v[120:123], v[0:3], 0
	v_mfma_f32_16x16x32_bf16 v[100:103], v[120:123], v[8:11], 0
	s_waitcnt lgkmcnt(4)
	v_mfma_f32_16x16x32_bf16 v[84:87], v[124:127], v[4:7], v[84:87]
	v_mfma_f32_16x16x32_bf16 v[100:103], v[124:127], v[12:15], v[100:103]
	s_waitcnt lgkmcnt(3)
	v_mfma_f32_16x16x32_bf16 v[88:91], v[128:131], v[0:3], 0
	v_mfma_f32_16x16x32_bf16 v[104:107], v[128:131], v[8:11], 0
	s_waitcnt lgkmcnt(2)
	v_mfma_f32_16x16x32_bf16 v[88:91], v[132:135], v[4:7], v[88:91]
	v_mfma_f32_16x16x32_bf16 v[104:107], v[132:135], v[12:15], v[104:107]
	s_waitcnt lgkmcnt(1)
; DEVI unsigned pack2(float a, float b) { return (unsigned)f2bf(a) | ((unsigned)f2bf(b) << 16); }
; DEVI float fexp2(float x) { return __builtin_amdgcn_exp2f(x); }
; template <int DH, int NQ, int LDK, class MaskF>
; DEVI void attn_qk(const u16* sK, const bf16x8 (&qf)[NQ][DH / 32], f32x4 (&o)[NQ][DH / 16], float (&m)[NQ], float (&l)[NQ],
;                   float c2, int lane, MaskF valid, bf16x8 (&pb)[NQ][2]) {
;     ...
;   for (int qt = 0; qt < NQ; ++qt) {
;     float mx = -1e30f;
; #pragma unroll
;     for (int kt = 0; kt < 4; ++kt)
; #pragma unroll
;       for (int r = 0; r < 4; ++r) {
;         const bool v = valid(qt, 16 * kt + 4 * quad + r);
;         const float sv = v ? s[qt][kt][r] : -1e30f;
;         s[qt][kt][r] = sv;
;         mx = fmaxf(mx, sv);
;       }
;     mx = fmaxf(mx, __shfl_xor(mx, 16));
;     mx = fmaxf(mx, __shfl_xor(mx, 32));
;     const float mn = fmaxf(m[qt], mx);
;     const float alpha = fexp2((m[qt] - mn) * c2);
;     m[qt] = mn;
;     const float mc = fmaxf(mn, -1e20f) * c2;
;     float ps = 0.f;
; #pragma unroll
;     for (int kt = 0; kt < 4; ++kt)
; #pragma unroll
;       for (int r = 0; r < 4; ++r) {
;         const float pv = fexp2(__builtin_fmaf(s[qt][kt][r], c2, -mc));
;         ps += pv;
;         s[qt][kt][r] = pv;
;       }
;     l[qt] = l[qt] * alpha + ps;
; #pragma unroll
;     for (int dt = 0; dt < DH / 16; ++dt) o[qt][dt] *= alpha;
; #pragma unroll
;     for (int kk = 0; kk < 2; ++kk) {
;       union { bf16x8 v; unsigned u[4]; } cv;
;       cv.u[0] = pack2(s[qt][2 * kk][0], s[qt][2 * kk][1]);
;       cv.u[1] = pack2(s[qt][2 * kk][2], s[qt][2 * kk][3]);
;       cv.u[2] = pack2(s[qt][2 * kk + 1][0], s[qt][2 * kk + 1][1]);
;       cv.u[3] = pack2(s[qt][2 * kk + 1][2], s[qt][2 * kk + 1][3]);
;       pb[qt][kk] = cv.v;
;     }
;   }
	v_mfma_f32_16x16x32_bf16 v[92:95], v[136:139], v[0:3], 0
	v_mfma_f32_16x16x32_bf16 v[108:111], v[136:139], v[8:11], 0
	s_waitcnt lgkmcnt(0)
	v_mfma_f32_16x16x32_bf16 v[92:95], v[140:143], v[4:7], v[92:95]
	v_mfma_f32_16x16x32_bf16 v[108:111], v[140:143], v[12:15], v[108:111]
	ds_read_b64 v[112:113], v231 offset:0
	ds_read_b64 v[114:115], v233 offset:0
	ds_read_b64 v[116:117], v232 offset:0
	ds_read_b64 v[118:119], v234 offset:0
	ds_read_b64 v[120:121], v231 offset:2048
	ds_read_b64 v[122:123], v233 offset:2048
	ds_read_b64 v[124:125], v232 offset:2048
	ds_read_b64 v[126:127], v234 offset:2048
	s_nop 3
	v_subrev_u32_e32 v222, s30, v207
	v_subrev_u32_e32 v223, 0, v222
	v_cmp_ge_u32_e64 s[32:33], s41, v223
	v_subrev_u32_e32 v224, 1, v222
	v_cmp_ge_u32_e64 s[34:35], s41, v224
	v_subrev_u32_e32 v225, 2, v222
	v_cmp_ge_u32_e64 s[36:37], s41, v225
	v_subrev_u32_e32 v226, 3, v222
	v_cmp_ge_u32_e64 s[38:39], s41, v226
	v_cndmask_b32_e64 v80, v230, v80, s[32:33]
	v_cndmask_b32_e64 v81, v230, v81, s[34:35]
	v_cndmask_b32_e64 v82, v230, v82, s[36:37]
	v_cndmask_b32_e64 v83, v230, v83, s[38:39]
	v_subrev_u32_e32 v223, 16, v222
	v_cmp_ge_u32_e64 s[32:33], s41, v223
	v_subrev_u32_e32 v224, 17, v222
	v_cmp_ge_u32_e64 s[34:35], s41, v224
	v_subrev_u32_e32 v225, 18, v222
	v_cmp_ge_u32_e64 s[36:37], s41, v225
	v_subrev_u32_e32 v226, 19, v222
	v_cmp_ge_u32_e64 s[38:39], s41, v226
	v_cndmask_b32_e64 v84, v230, v84, s[32:33]
	v_cndmask_b32_e64 v85, v230, v85, s[34:35]
	v_cndmask_b32_e64 v86, v230, v86, s[36:37]
	v_cndmask_b32_e64 v87, v230, v87, s[38:39]
	v_subrev_u32_e32 v223, 32, v222
	v_cmp_ge_u32_e64 s[32:33], s41, v223
	v_subrev_u32_e32 v224, 33, v222
	v_cmp_ge_u32_e64 s[34:35], s41, v224
	v_subrev_u32_e32 v225, 34, v222
	v_cmp_ge_u32_e64 s[36:37], s41, v225
	v_subrev_u32_e32 v226, 35, v222
	v_cmp_ge_u32_e64 s[38:39], s41, v226
	v_cndmask_b32_e64 v88, v230, v88, s[32:33]
	v_cndmask_b32_e64 v89, v230, v89, s[34:35]
	v_cndmask_b32_e64 v90, v230, v90, s[36:37]
	v_cndmask_b32_e64 v91, v230, v91, s[38:39]
	v_subrev_u32_e32 v223, 48, v222
	v_cmp_ge_u32_e64 s[32:33], s41, v223
	v_subrev_u32_e32 v224, 49, v222
	v_cmp_ge_u32_e64 s[34:35], s41, v224
	v_subrev_u32_e32 v225, 50, v222
	v_cmp_ge_u32_e64 s[36:37], s41, v225
	v_subrev_u32_e32 v226, 51, v222
	v_cmp_ge_u32_e64 s[38:39], s41, v226
	v_cndmask_b32_e64 v92, v230, v92, s[32:33]
	v_cndmask_b32_e64 v93, v230, v93, s[34:35]
	v_cndmask_b32_e64 v94, v230, v94, s[36:37]
	v_cndmask_b32_e64 v95, v230, v95, s[38:39]
	v_max3_f32 v215, v80, v81, v82
	v_max3_f32 v215, v215, v83, v84
	v_max3_f32 v215, v215, v85, v86
	v_max3_f32 v215, v215, v87, v88
	v_max3_f32 v215, v215, v89, v90
	v_max3_f32 v215, v215, v91, v92
	v_max3_f32 v215, v215, v93, v94
	v_max_f32_e32 v215, v95, v215
	ds_bpermute_b32 v217, v195, v215
	s_waitcnt lgkmcnt(0)
	v_max_f32_e32 v215, v217, v215
	v_mov_b32_e32 v217, v215
	v_mov_b32_e32 v218, v215
	s_nop 1
	v_permlane32_swap_b32_e32 v217, v218
	v_max_f32_e32 v215, v217, v218
	v_max_f32_e32 v219, v182, v215
	v_sub_f32_e32 v216, v182, v219
	v_mul_f32_e32 v216, v200, v216
	v_exp_f32_e32 v216, v216
	v_mov_b32_e32 v182, v219
	v_max_f32_e32 v220, 0xe0ad78ec, v219
	v_mul_f32_e32 v220, 0xbe38aa3b, v220
	v_fma_f32 v80, v80, v200, v220
	v_exp_f32_e32 v80, v80
	v_fma_f32 v81, v81, v200, v220
	v_exp_f32_e32 v81, v81
	v_fma_f32 v82, v82, v200, v220
	v_exp_f32_e32 v82, v82
	v_fma_f32 v83, v83, v200, v220
	v_exp_f32_e32 v83, v83
	v_fma_f32 v84, v84, v200, v220
	v_exp_f32_e32 v84, v84
	v_fma_f32 v85, v85, v200, v220
	v_exp_f32_e32 v85, v85
	v_fma_f32 v86, v86, v200, v220
	v_exp_f32_e32 v86, v86
	v_fma_f32 v87, v87, v200, v220
	v_exp_f32_e32 v87, v87
	v_fma_f32 v88, v88, v200, v220
	v_exp_f32_e32 v88, v88
	v_fma_f32 v89, v89, v200, v220
	v_exp_f32_e32 v89, v89
	v_fma_f32 v90, v90, v200, v220
	v_exp_f32_e32 v90, v90
	v_fma_f32 v91, v91, v200, v220
	v_exp_f32_e32 v91, v91
	v_fma_f32 v92, v92, v200, v220
	v_exp_f32_e32 v92, v92
	v_fma_f32 v93, v93, v200, v220
	v_exp_f32_e32 v93, v93
	v_fma_f32 v94, v94, v200, v220
	v_exp_f32_e32 v94, v94
	v_fma_f32 v95, v95, v200, v220
	v_exp_f32_e32 v95, v95
	s_nop 0
	v_add_f32_e32 v221, v80, v81
	v_add_f32_e32 v221, v82, v221
	v_add_f32_e32 v221, v83, v221
	v_add_f32_e32 v221, v84, v221
	v_add_f32_e32 v221, v85, v221
	v_add_f32_e32 v221, v86, v221
	v_add_f32_e32 v221, v87, v221
	v_add_f32_e32 v221, v88, v221
	v_add_f32_e32 v221, v89, v221
	v_add_f32_e32 v221, v90, v221
	v_add_f32_e32 v221, v91, v221
	v_add_f32_e32 v221, v92, v221
	v_add_f32_e32 v221, v93, v221
	v_add_f32_e32 v221, v94, v221
	v_add_f32_e32 v221, v95, v221
	v_mul_f32_e32 v16, v216, v16
	v_mul_f32_e32 v17, v216, v17
	v_mul_f32_e32 v18, v216, v18
	v_mul_f32_e32 v19, v216, v19
	v_mul_f32_e32 v20, v216, v20
	v_mul_f32_e32 v21, v216, v21
	v_mul_f32_e32 v22, v216, v22
	v_mul_f32_e32 v23, v216, v23
	v_mul_f32_e32 v24, v216, v24
	v_mul_f32_e32 v25, v216, v25
	v_mul_f32_e32 v26, v216, v26
	v_mul_f32_e32 v27, v216, v27
	v_mul_f32_e32 v28, v216, v28
	v_mul_f32_e32 v29, v216, v29
	v_mul_f32_e32 v30, v216, v30
	v_mul_f32_e32 v31, v216, v31
	v_fma_f32 v184, v184, v216, v221
	v_cvt_pk_bf16_f32 v144, v80, v81
	v_cvt_pk_bf16_f32 v145, v82, v83
	v_cvt_pk_bf16_f32 v146, v84, v85
	v_cvt_pk_bf16_f32 v147, v86, v87
	v_cvt_pk_bf16_f32 v148, v88, v89
	v_cvt_pk_bf16_f32 v149, v90, v91
	v_cvt_pk_bf16_f32 v150, v92, v93
	v_cvt_pk_bf16_f32 v151, v94, v95
	v_subrev_u32_e32 v222, s30, v208
	v_subrev_u32_e32 v223, 0, v222
	v_cmp_ge_u32_e64 s[32:33], s41, v223
	v_subrev_u32_e32 v224, 1, v222
	v_cmp_ge_u32_e64 s[34:35], s41, v224
	v_subrev_u32_e32 v225, 2, v222
	v_cmp_ge_u32_e64 s[36:37], s41, v225
	v_subrev_u32_e32 v226, 3, v222
	v_cmp_ge_u32_e64 s[38:39], s41, v226
; template <int DH, int NQ, int LDK, class MaskF>
; DEVI void attn_qk(const u16* sK, const bf16x8 (&qf)[NQ][DH / 32], f32x4 (&o)[NQ][DH / 16], float (&m)[NQ], float (&l)[NQ],
;                   float c2, int lane, MaskF valid, bf16x8 (&pb)[NQ][2]) {
;     ...
;   for (int qt = 0; qt < NQ; ++qt) {
;     float mx = -1e30f;
; #pragma unroll
;     for (int kt = 0; kt < 4; ++kt)
; #pragma unroll
;       for (int r = 0; r < 4; ++r) {
;         const bool v = valid(qt, 16 * kt + 4 * quad + r);
;         const float sv = v ? s[qt][kt][r] : -1e30f;
;         s[qt][kt][r] = sv;
;         mx = fmaxf(mx, sv);
;       }
;     mx = fmaxf(mx, __shfl_xor(mx, 16));
;     mx = fmaxf(mx, __shfl_xor(mx, 32));
;     const float mn = fmaxf(m[qt], mx);
;     const float alpha = fexp2((m[qt] - mn) * c2);
;     m[qt] = mn;
;     const float mc = fmaxf(mn, -1e20f) * c2;
;     float ps = 0.f;
; #pragma unroll
;     for (int kt = 0; kt < 4; ++kt)
; #pragma unroll
;       for (int r = 0; r < 4; ++r) {
;         const float pv = fexp2(__builtin_fmaf(s[qt][kt][r], c2, -mc));
;         ps += pv;
;         s[qt][kt][r] = pv;
;       }
;     l[qt] = l[qt] * alpha + ps;
; #pragma unroll
;     for (int dt = 0; dt < DH / 16; ++dt) o[qt][dt] *= alpha;
; #pragma unroll
;     for (int kk = 0; kk < 2; ++kk) {
;       union { bf16x8 v; unsigned u[4]; } cv;
;       cv.u[0] = pack2(s[qt][2 * kk][0], s[qt][2 * kk][1]);
;       cv.u[1] = pack2(s[qt][2 * kk][2], s[qt][2 * kk][3]);
;       cv.u[2] = pack2(s[qt][2 * kk + 1][0], s[qt][2 * kk + 1][1]);
;       cv.u[3] = pack2(s[qt][2 * kk + 1][2], s[qt][2 * kk + 1][3]);
;       pb[qt][kk] = cv.v;
;     }
;   }
; }
; template <int DH, int NQ, int LDV>
; DEVI void attn_pv(const u16* sVt, const bf16x8 (&pb)[NQ][2], f32x4 (&o)[NQ][DH / 16], int lane) {
;   const int col = lane & 15, quad = lane >> 4;
;   __builtin_amdgcn_s_setprio(1);
; #pragma unroll
;   for (int dt = 0; dt < DH / 16; ++dt) {
; #pragma unroll
;     for (int kk = 0; kk < 2; ++kk) {
;       union { bf16x8 v; uint2 h[2]; } cv;
;       cv.h[0] = *(const uint2*)(sVt + (16 * dt + col) * LDV + 32 * kk + 4 * quad);
;       cv.h[1] = *(const uint2*)(sVt + (16 * dt + col) * LDV + 32 * kk + 16 + 4 * quad);
; #pragma unroll
;       for (int qt = 0; qt < NQ; ++qt) o[qt][dt] = mfma16(cv.v, pb[qt][kk], o[qt][dt]);
;     }
;   }
;   __builtin_amdgcn_s_setprio(0);
	v_cndmask_b32_e64 v96, v230, v96, s[32:33]
	v_cndmask_b32_e64 v97, v230, v97, s[34:35]
	v_cndmask_b32_e64 v98, v230, v98, s[36:37]
	v_cndmask_b32_e64 v99, v230, v99, s[38:39]
	v_subrev_u32_e32 v223, 16, v222
	v_cmp_ge_u32_e64 s[32:33], s41, v223
	v_subrev_u32_e32 v224, 17, v222
	v_cmp_ge_u32_e64 s[34:35], s41, v224
	v_subrev_u32_e32 v225, 18, v222
	v_cmp_ge_u32_e64 s[36:37], s41, v225
	v_subrev_u32_e32 v226, 19, v222
	v_cmp_ge_u32_e64 s[38:39], s41, v226
	v_cndmask_b32_e64 v100, v230, v100, s[32:33]
	v_cndmask_b32_e64 v101, v230, v101, s[34:35]
	v_cndmask_b32_e64 v102, v230, v102, s[36:37]
	v_cndmask_b32_e64 v103, v230, v103, s[38:39]
	v_subrev_u32_e32 v223, 32, v222
	v_cmp_ge_u32_e64 s[32:33], s41, v223
	v_subrev_u32_e32 v224, 33, v222
	v_cmp_ge_u32_e64 s[34:35], s41, v224
	v_subrev_u32_e32 v225, 34, v222
	v_cmp_ge_u32_e64 s[36:37], s41, v225
	v_subrev_u32_e32 v226, 35, v222
	v_cmp_ge_u32_e64 s[38:39], s41, v226
	v_cndmask_b32_e64 v104, v230, v104, s[32:33]
	v_cndmask_b32_e64 v105, v230, v105, s[34:35]
	v_cndmask_b32_e64 v106, v230, v106, s[36:37]
	v_cndmask_b32_e64 v107, v230, v107, s[38:39]
	v_subrev_u32_e32 v223, 48, v222
	v_cmp_ge_u32_e64 s[32:33], s41, v223
	v_subrev_u32_e32 v224, 49, v222
	v_cmp_ge_u32_e64 s[34:35], s41, v224
	v_subrev_u32_e32 v225, 50, v222
	v_cmp_ge_u32_e64 s[36:37], s41, v225
	v_subrev_u32_e32 v226, 51, v222
	v_cmp_ge_u32_e64 s[38:39], s41, v226
	v_cndmask_b32_e64 v108, v230, v108, s[32:33]
	v_cndmask_b32_e64 v109, v230, v109, s[34:35]
	v_cndmask_b32_e64 v110, v230, v110, s[36:37]
	v_cndmask_b32_e64 v111, v230, v111, s[38:39]
	v_max3_f32 v215, v96, v97, v98
	v_max3_f32 v215, v215, v99, v100
	v_max3_f32 v215, v215, v101, v102
	v_max3_f32 v215, v215, v103, v104
	v_max3_f32 v215, v215, v105, v106
	v_max3_f32 v215, v215, v107, v108
	v_max3_f32 v215, v215, v109, v110
	v_max_f32_e32 v215, v111, v215
	ds_bpermute_b32 v217, v195, v215
	s_waitcnt lgkmcnt(0)
	v_max_f32_e32 v215, v217, v215
	v_mov_b32_e32 v217, v215
	v_mov_b32_e32 v218, v215
	s_nop 1
	v_permlane32_swap_b32_e32 v217, v218
	v_max_f32_e32 v215, v217, v218
	v_max_f32_e32 v219, v183, v215
	v_sub_f32_e32 v216, v183, v219
	v_mul_f32_e32 v216, v200, v216
	v_exp_f32_e32 v216, v216
	v_mov_b32_e32 v183, v219
	v_max_f32_e32 v220, 0xe0ad78ec, v219
	v_mul_f32_e32 v220, 0xbe38aa3b, v220
	v_fma_f32 v96, v96, v200, v220
	v_exp_f32_e32 v96, v96
	v_fma_f32 v97, v97, v200, v220
	v_exp_f32_e32 v97, v97
	v_fma_f32 v98, v98, v200, v220
	v_exp_f32_e32 v98, v98
	v_fma_f32 v99, v99, v200, v220
	v_exp_f32_e32 v99, v99
	v_fma_f32 v100, v100, v200, v220
	v_exp_f32_e32 v100, v100
	v_fma_f32 v101, v101, v200, v220
	v_exp_f32_e32 v101, v101
	v_fma_f32 v102, v102, v200, v220
	v_exp_f32_e32 v102, v102
	v_fma_f32 v103, v103, v200, v220
	v_exp_f32_e32 v103, v103
	v_fma_f32 v104, v104, v200, v220
	v_exp_f32_e32 v104, v104
	v_fma_f32 v105, v105, v200, v220
	v_exp_f32_e32 v105, v105
	v_fma_f32 v106, v106, v200, v220
	v_exp_f32_e32 v106, v106
	v_fma_f32 v107, v107, v200, v220
	v_exp_f32_e32 v107, v107
	v_fma_f32 v108, v108, v200, v220
	v_exp_f32_e32 v108, v108
	v_fma_f32 v109, v109, v200, v220
	v_exp_f32_e32 v109, v109
	v_fma_f32 v110, v110, v200, v220
	v_exp_f32_e32 v110, v110
	v_fma_f32 v111, v111, v200, v220
	v_exp_f32_e32 v111, v111
	s_nop 0
	v_add_f32_e32 v221, v96, v97
	v_add_f32_e32 v221, v98, v221
	v_add_f32_e32 v221, v99, v221
	v_add_f32_e32 v221, v100, v221
	v_add_f32_e32 v221, v101, v221
	v_add_f32_e32 v221, v102, v221
	v_add_f32_e32 v221, v103, v221
	v_add_f32_e32 v221, v104, v221
	v_add_f32_e32 v221, v105, v221
	v_add_f32_e32 v221, v106, v221
	v_add_f32_e32 v221, v107, v221
	v_add_f32_e32 v221, v108, v221
	v_add_f32_e32 v221, v109, v221
	v_add_f32_e32 v221, v110, v221
	v_add_f32_e32 v221, v111, v221
	v_mul_f32_e32 v32, v216, v32
	v_mul_f32_e32 v33, v216, v33
	v_mul_f32_e32 v34, v216, v34
	v_mul_f32_e32 v35, v216, v35
	v_mul_f32_e32 v36, v216, v36
	v_mul_f32_e32 v37, v216, v37
	v_mul_f32_e32 v38, v216, v38
	v_mul_f32_e32 v39, v216, v39
	v_mul_f32_e32 v40, v216, v40
	v_mul_f32_e32 v41, v216, v41
	v_mul_f32_e32 v42, v216, v42
	v_mul_f32_e32 v43, v216, v43
	v_mul_f32_e32 v44, v216, v44
	v_mul_f32_e32 v45, v216, v45
	v_mul_f32_e32 v46, v216, v46
	v_mul_f32_e32 v47, v216, v47
	v_fma_f32 v185, v185, v216, v221
	v_cvt_pk_bf16_f32 v152, v96, v97
	v_cvt_pk_bf16_f32 v153, v98, v99
	v_cvt_pk_bf16_f32 v154, v100, v101
	v_cvt_pk_bf16_f32 v155, v102, v103
	v_cvt_pk_bf16_f32 v156, v104, v105
	v_cvt_pk_bf16_f32 v157, v106, v107
	v_cvt_pk_bf16_f32 v158, v108, v109
	v_cvt_pk_bf16_f32 v159, v110, v111
	ds_read_b64 v[128:129], v231 offset:4096
	ds_read_b64 v[130:131], v233 offset:4096
	ds_read_b64 v[132:133], v232 offset:4096
	ds_read_b64 v[134:135], v234 offset:4096
	ds_read_b64 v[136:137], v231 offset:6144
	ds_read_b64 v[138:139], v233 offset:6144
	ds_read_b64 v[140:141], v232 offset:6144
	ds_read_b64 v[142:143], v234 offset:6144
	s_waitcnt lgkmcnt(8)
	v_mfma_f32_16x16x32_bf16 v[16:19], v[112:115], v[144:147], v[16:19]
	v_mfma_f32_16x16x32_bf16 v[32:35], v[112:115], v[152:155], v[32:35]
	v_mfma_f32_16x16x32_bf16 v[16:19], v[116:119], v[148:151], v[16:19]
	v_mfma_f32_16x16x32_bf16 v[32:35], v[116:119], v[156:159], v[32:35]
	v_mfma_f32_16x16x32_bf16 v[20:23], v[120:123], v[144:147], v[20:23]
	v_mfma_f32_16x16x32_bf16 v[36:39], v[120:123], v[152:155], v[36:39]
	v_mfma_f32_16x16x32_bf16 v[20:23], v[124:127], v[148:151], v[20:23]
	v_mfma_f32_16x16x32_bf16 v[36:39], v[124:127], v[156:159], v[36:39]
	s_waitcnt lgkmcnt(0)
	v_mfma_f32_16x16x32_bf16 v[24:27], v[128:131], v[144:147], v[24:27]
	v_mfma_f32_16x16x32_bf16 v[40:43], v[128:131], v[152:155], v[40:43]
	v_mfma_f32_16x16x32_bf16 v[24:27], v[132:135], v[148:151], v[24:27]
	v_mfma_f32_16x16x32_bf16 v[40:43], v[132:135], v[156:159], v[40:43]
	v_mfma_f32_16x16x32_bf16 v[28:31], v[136:139], v[144:147], v[28:31]
	v_mfma_f32_16x16x32_bf16 v[44:47], v[136:139], v[152:155], v[44:47]
	v_mfma_f32_16x16x32_bf16 v[28:31], v[140:143], v[148:151], v[28:31]
	v_mfma_f32_16x16x32_bf16 v[44:47], v[140:143], v[156:159], v[44:47]

; template <bool DB, class AF>
; DEVI void gemm_mainloop(int tid, u16* sA, u16* sB, AF af, const u16* __restrict__ Bt, int ldb, int m0, int n0, int nk,
;                         f32x4 (&acc)[4][4]) {
;     ...
;   const int wm = w >> 1, wn = w & 1, col = lane & 15, quad = lane >> 4;
; #pragma unroll
;   for (int i = 0; i < 4; ++i)
; #pragma unroll
;     for (int j = 0; j < 4; ++j) acc[i][j] = f32x4{0.f, 0.f, 0.f, 0.f};
;   uint4 ra0, ra1, ra2, ra3, rb0, rb1, rb2, rb3;
;   const int lrow = tid >> 3, lkc = (tid & 7) << 3;
;   const u16* bbase = Bt + (size_t)(n0 + lrow) * ldb + lkc;
;     ...
;   if (DB) {
;     const int srow = 8 * w + (lane >> 3);
;     const int spc = lane & 7;
;     ...
;     STAGE_(0, 0)
; #pragma unroll 1
;     for (int kt = 0; kt < nk; kt += 2) {
.LBB0_892:
	v_mov_b32_e32 v105, v210
	s_ashr_i32 s4, s11, 31
	s_lshr_b32 s4, s4, 29
	v_ashrrev_i32_e32 v6, 6, v105
	s_add_i32 s4, s11, s4
	v_lshlrev_b32_e32 v7, 3, v6
	v_bfe_u32 v8, v105, 3, 3
	s_and_b32 s17, s4, -8
	v_or_b32_e32 v9, v7, v8
	s_ashr_i32 s19, s4, 3
	s_or_b32 s18, s17, s13
	v_lshrrev_b32_e32 v10, 1, v9
	s_and_b64 s[4:5], s[2:3], exec
	v_xor_b32_e32 v0, v10, v105
	s_cselect_b32 s4, s18, s19
	v_lshlrev_b32_e32 v0, 4, v0
	s_lshl_b32 s18, s4, 7
	v_and_b32_e32 v64, 0x70, v0
	s_sub_i32 s5, s11, s17
	s_waitcnt lgkmcnt(0)
	v_lshl_add_u64 v[0:1], s[70:71], 0, v[64:65]
	v_add_u32_e32 v4, s18, v9
	s_lshl_b32 s17, s5, 7
	v_mad_i64_i32 v[4:5], s[4:5], v4, s15, v[0:1]
	v_lshlrev_b32_e32 v106, 10, v6
	v_readlane_b32 s72, v248, 58
	v_readfirstlane_b32 s4, v106
	v_readlane_b32 s84, v247, 6
	v_readlane_b32 s85, v247, 7
	s_mov_b32 m0, s4
	v_add_u32_e32 v107, 0x4000, v106
	v_lshl_add_u64 v[2:3], s[84:85], 0, v[64:65]
	global_load_lds_dwordx4 v[4:5], off
	v_add_u32_e32 v4, s17, v9
	v_mad_i64_i32 v[4:5], s[4:5], v4, s15, v[2:3]
	v_readfirstlane_b32 s4, v107
	s_mov_b32 m0, s4
	v_add_u32_e32 v11, 32, v9
	global_load_lds_dwordx4 v[4:5], off
	v_add_u32_e32 v4, s18, v11
	v_mad_i64_i32 v[4:5], s[4:5], v4, s15, v[0:1]
	v_add_u32_e32 v108, 0x1000, v106
	v_add_u32_e32 v109, 0x5000, v106
	v_readfirstlane_b32 s4, v108
	s_mov_b32 m0, s4
	v_add_u32_e32 v110, 0x2000, v106
	global_load_lds_dwordx4 v[4:5], off
	v_add_u32_e32 v4, s17, v11
	v_mad_i64_i32 v[4:5], s[4:5], v4, s15, v[2:3]
	v_readfirstlane_b32 s4, v109
	s_mov_b32 m0, s4
	v_add_u32_e32 v11, 64, v9
	global_load_lds_dwordx4 v[4:5], off
	v_add_u32_e32 v4, s18, v11
	v_mad_i64_i32 v[4:5], s[4:5], v4, s15, v[0:1]
	v_readfirstlane_b32 s4, v110
	s_mov_b32 m0, s4
	v_add_u32_e32 v111, 0x6000, v106
	global_load_lds_dwordx4 v[4:5], off
	v_add_u32_e32 v4, s17, v11
	v_mad_i64_i32 v[4:5], s[4:5], v4, s15, v[2:3]
	v_readfirstlane_b32 s4, v111
	s_mov_b32 m0, s4
	s_nop 0
	v_add_u32_e32 v112, 0x3000, v106
	global_load_lds_dwordx4 v[4:5], off
	v_add_u32_e32 v4, 0x60, v9
	v_add_u32_e32 v5, s18, v4
	v_mad_i64_i32 v[0:1], s[4:5], v5, s15, v[0:1]
	v_readfirstlane_b32 s4, v112
	s_mov_b32 m0, s4
	v_add_u32_e32 v113, 0x7000, v106
	global_load_lds_dwordx4 v[0:1], off
	v_add_u32_e32 v0, s17, v4
	v_mad_i64_i32 v[0:1], s[4:5], v0, s15, v[2:3]
	v_readfirstlane_b32 s4, v113
	s_mov_b32 m0, s4
	v_bfe_u32 v104, v105, 4, 2
	global_load_lds_dwordx4 v[0:1], off
	v_lshrrev_b32_e32 v0, 1, v105
	v_bfe_u32 v1, v105, 1, 3
	v_bitop3_b32 v0, v104, v0, 7 bitop3:0x78
	v_lshlrev_b32_e32 v2, 6, v105
	v_lshlrev_b32_e32 v5, 13, v6
	v_bitop3_b32 v1, v104, v1, 4 bitop3:0x36
	v_lshlrev_b32_e32 v0, 4, v0
	v_and_b32_e32 v2, 0xffffe000, v2
	v_and_b32_e32 v5, 0x2000, v5
	v_lshlrev_b32_e32 v1, 4, v1
	v_or_b32_e32 v4, v0, v2
	v_or_b32_e32 v0, v0, v5
	v_or_b32_e32 v2, v1, v2
	v_or_b32_e32 v1, v1, v5
	v_bitop3_b32 v5, v10, 7, v105 bitop3:0x48
	s_lshl_b32 s20, s11, 7
	v_lshlrev_b32_e32 v64, 4, v5
	v_or_b32_e32 v5, s20, v8
	v_add_u32_e32 v5, v5, v7
	s_lshl_b32 s19, s19, 10
	v_subrev_u32_e32 v5, s19, v5
	v_mad_i64_i32 v[70:71], s[4:5], v5, s15, v[66:67]
	v_or_b32_e32 v5, 32, v8
	v_or_b32_e32 v6, s20, v5
	v_add_u32_e32 v6, v6, v7
	v_subrev_u32_e32 v6, s19, v6
	v_mad_i64_i32 v[72:73], s[4:5], v6, s15, v[66:67]
	v_or_b32_e32 v6, 64, v8
	v_or_b32_e32 v9, s20, v6
	v_add_u32_e32 v9, v9, v7
	v_or_b32_e32 v5, s18, v5
	v_subrev_u32_e32 v9, s19, v9
	v_add_u32_e32 v5, v5, v7
	v_mad_i64_i32 v[74:75], s[4:5], v9, s15, v[66:67]
	v_or_b32_e32 v9, 0x60, v8
	v_mad_i64_i32 v[80:81], s[4:5], v5, s15, v[68:69]
	v_or_b32_e32 v5, s18, v6
	v_or_b32_e32 v10, s20, v9
	v_add_u32_e32 v5, v5, v7
	v_lshlrev_b32_e32 v3, 7, v105
	v_add_u32_e32 v10, v10, v7
	v_or_b32_e32 v8, s18, v8
	v_mad_i64_i32 v[82:83], s[4:5], v5, s15, v[68:69]
	v_or_b32_e32 v5, s18, v9
	v_and_b32_e32 v3, 0x780, v3
	v_subrev_u32_e32 v10, s19, v10
	v_add_u32_e32 v8, v8, v7
	v_add_u32_e32 v5, v5, v7
	v_mad_i64_i32 v[76:77], s[4:5], v10, s15, v[66:67]
	v_mad_i64_i32 v[78:79], s[4:5], v8, s15, v[68:69]
	v_mad_i64_i32 v[84:85], s[4:5], v5, s15, v[68:69]
	s_mov_b32 s19, 0
	v_add_u32_e32 v114, 0x8000, v106
	v_add_u32_e32 v115, 0xc000, v106
	v_add_u32_e32 v116, 0x9000, v106
	v_add_u32_e32 v117, 0xd000, v106
	v_add_u32_e32 v118, 0xa000, v106
	v_add_u32_e32 v119, 0xe000, v106
	v_add_u32_e32 v120, 0xb000, v106
	v_add_u32_e32 v121, 0xf000, v106
	v_add_u32_e32 v122, v4, v3
	v_add_u32_e32 v123, v0, v3
	v_add_u32_e32 v124, v2, v3
	v_add_u32_e32 v125, v1, v3
	v_mov_b32_e32 v0, v65
	v_mov_b32_e32 v1, v65
	v_mov_b32_e32 v2, v65
	v_mov_b32_e32 v3, v65
	v_mov_b32_e32 v16, v65
	v_mov_b32_e32 v17, v65
	v_mov_b32_e32 v18, v65
	v_mov_b32_e32 v19, v65
	v_mov_b32_e32 v32, v65
	v_mov_b32_e32 v33, v65
	v_mov_b32_e32 v34, v65
	v_mov_b32_e32 v35, v65
	v_mov_b32_e32 v48, v65
	v_mov_b32_e32 v49, v65
	v_mov_b32_e32 v50, v65
	v_mov_b32_e32 v51, v65
	v_mov_b32_e32 v4, v65
	v_mov_b32_e32 v5, v65
	v_mov_b32_e32 v6, v65
	v_mov_b32_e32 v7, v65
	v_mov_b32_e32 v20, v65
	v_mov_b32_e32 v21, v65
	v_mov_b32_e32 v22, v65
	v_mov_b32_e32 v23, v65
	v_mov_b32_e32 v36, v65
	v_mov_b32_e32 v37, v65
	v_mov_b32_e32 v38, v65
	v_mov_b32_e32 v39, v65
	v_mov_b32_e32 v52, v65
	v_mov_b32_e32 v53, v65
	v_mov_b32_e32 v54, v65
	v_mov_b32_e32 v55, v65
	v_mov_b32_e32 v8, v65
	v_mov_b32_e32 v9, v65
	v_mov_b32_e32 v10, v65
	v_mov_b32_e32 v11, v65
	v_mov_b32_e32 v24, v65
	v_mov_b32_e32 v25, v65
	v_mov_b32_e32 v26, v65
	v_mov_b32_e32 v27, v65
	v_mov_b32_e32 v40, v65
	v_mov_b32_e32 v41, v65
	v_mov_b32_e32 v42, v65
	v_mov_b32_e32 v43, v65
	v_mov_b32_e32 v56, v65
	v_mov_b32_e32 v57, v65
	v_mov_b32_e32 v58, v65
	v_mov_b32_e32 v59, v65
	v_mov_b32_e32 v12, v65
	v_mov_b32_e32 v13, v65
	v_mov_b32_e32 v14, v65
	v_mov_b32_e32 v15, v65
	v_mov_b32_e32 v28, v65
	v_mov_b32_e32 v29, v65
	v_mov_b32_e32 v30, v65
	v_mov_b32_e32 v31, v65
	v_mov_b32_e32 v44, v65
	v_mov_b32_e32 v45, v65
	v_mov_b32_e32 v46, v65
	v_mov_b32_e32 v47, v65
	v_mov_b32_e32 v60, v65
	v_mov_b32_e32 v61, v65
	v_mov_b32_e32 v62, v65
	v_mov_b32_e32 v63, v65
	v_readlane_b32 s73, v248, 59
	v_readlane_b32 s74, v248, 60
	v_readlane_b32 s75, v248, 61
	v_readlane_b32 s76, v248, 62
	v_readlane_b32 s77, v248, 63
	v_readlane_b32 s78, v247, 0
	v_readlane_b32 s79, v247, 1
	v_readlane_b32 s80, v247, 2
	v_readlane_b32 s81, v247, 3
	v_readlane_b32 s82, v247, 4
	v_readlane_b32 s83, v247, 5
	v_readlane_b32 s86, v247, 8
	v_readlane_b32 s87, v247, 9
	s_branch .LBB0_894

; template <bool DB, class AF>
; DEVI void gemm_mainloop(int tid, u16* sA, u16* sB, AF af, const u16* __restrict__ Bt, int ldb, int m0, int n0, int nk,
;                         f32x4 (&acc)[4][4]) {
;   const int lane = tid & 63, w = tid >> 6;
;   const int wm = w >> 1, wn = w & 1, col = lane & 15, quad = lane >> 4;
; #pragma unroll
;   for (int i = 0; i < 4; ++i)
; #pragma unroll
;     for (int j = 0; j < 4; ++j) acc[i][j] = f32x4{0.f, 0.f, 0.f, 0.f};
;   uint4 ra0, ra1, ra2, ra3, rb0, rb1, rb2, rb3;
;   const int lrow = tid >> 3, lkc = (tid & 7) << 3;
;   const u16* bbase = Bt + (size_t)(n0 + lrow) * ldb + lkc;
;     ...
;   if (DB) {
;     const int srow = 8 * w + (lane >> 3);
;     const int spc = lane & 7;
;     ...
;     STAGE_(0, 0)
; DEVI void phase_scaled(const Params& p, unsigned char* smem, const u16* A, const u16* Wt, int ntn, const float* ssq, u16* outp, int ldo) {
;     ...
;   XCD_TILE_LOOP(idx, 256, ntn) {
;     GEMM_LANE_VARS
;     const int mt = XCD_TILE_MT(idx, ntn), nt_ = XCD_TILE_NT(idx, ntn);
;     const int m0 = mt * 128, n0 = nt_ * 128;
;     f32x4 acc[4][4];
;     gemm_mainloop<true>(tid, sA, sB, ARow{A, LDA}, Wt, LDA, m0, n0, 16, acc);
.LBB0_962:
	v_mov_b32_e32 v104, v210
	s_ashr_i32 s8, s11, 31
	s_lshr_b32 s8, s8, 29
	v_ashrrev_i32_e32 v6, 6, v104
	s_add_i32 s8, s11, s8
	v_lshlrev_b32_e32 v7, 3, v6
	v_bfe_u32 v8, v104, 3, 3
	s_and_b32 s18, s8, -8
	v_or_b32_e32 v9, v7, v8
	s_ashr_i32 s20, s8, 3
	s_or_b32 s19, s18, s13
	v_lshrrev_b32_e32 v10, 1, v9
	s_and_b64 s[8:9], s[2:3], exec
	v_xor_b32_e32 v0, v10, v104
	s_cselect_b32 s8, s19, s20
	v_lshlrev_b32_e32 v0, 4, v0
	v_readlane_b32 s24, v248, 0
	s_lshl_b32 s19, s8, 7
	v_and_b32_e32 v64, 0x70, v0
	v_readlane_b32 s25, v248, 1
	s_sub_i32 s9, s11, s18
	v_add_u32_e32 v4, s19, v9
	v_lshl_add_u64 v[0:1], s[24:25], 0, v[64:65]
	s_lshl_b32 s18, s9, 7
	v_mad_i64_i32 v[4:5], s[8:9], v4, s15, v[0:1]
	v_lshlrev_b32_e32 v105, 10, v6
	v_readlane_b32 s72, v248, 58
	v_readfirstlane_b32 s8, v105
	v_readlane_b32 s86, v247, 8
	v_readlane_b32 s87, v247, 9
	s_mov_b32 m0, s8
	v_add_u32_e32 v106, 0x4000, v105
	v_lshl_add_u64 v[2:3], s[86:87], 0, v[64:65]
	global_load_lds_dwordx4 v[4:5], off
	v_add_u32_e32 v4, s18, v9
	v_mad_i64_i32 v[4:5], s[8:9], v4, s15, v[2:3]
	v_readfirstlane_b32 s8, v106
	s_mov_b32 m0, s8
	v_add_u32_e32 v11, 32, v9
	global_load_lds_dwordx4 v[4:5], off
	v_add_u32_e32 v4, s19, v11
	v_mad_i64_i32 v[4:5], s[8:9], v4, s15, v[0:1]
	v_add_u32_e32 v107, 0x1000, v105
	v_add_u32_e32 v108, 0x5000, v105
	v_readfirstlane_b32 s8, v107
	s_mov_b32 m0, s8
	v_add_u32_e32 v109, 0x2000, v105
	global_load_lds_dwordx4 v[4:5], off
	v_add_u32_e32 v4, s18, v11
	v_mad_i64_i32 v[4:5], s[8:9], v4, s15, v[2:3]
	v_readfirstlane_b32 s8, v108
	s_mov_b32 m0, s8
	v_add_u32_e32 v11, 64, v9
	global_load_lds_dwordx4 v[4:5], off
	v_add_u32_e32 v4, s19, v11
	v_mad_i64_i32 v[4:5], s[8:9], v4, s15, v[0:1]
	v_readfirstlane_b32 s8, v109
	s_mov_b32 m0, s8
	v_add_u32_e32 v110, 0x6000, v105
	global_load_lds_dwordx4 v[4:5], off
	v_add_u32_e32 v4, s18, v11
	v_mad_i64_i32 v[4:5], s[8:9], v4, s15, v[2:3]
	v_readfirstlane_b32 s8, v110
	s_mov_b32 m0, s8
	v_add_u32_e32 v111, 0x3000, v105
	global_load_lds_dwordx4 v[4:5], off
	v_add_u32_e32 v4, 0x60, v9
	v_add_u32_e32 v5, s19, v4
	v_mad_i64_i32 v[0:1], s[8:9], v5, s15, v[0:1]
	v_readfirstlane_b32 s8, v111
	s_mov_b32 m0, s8
	s_nop 0
	v_add_u32_e32 v112, 0x7000, v105
	global_load_lds_dwordx4 v[0:1], off
	v_add_u32_e32 v0, s18, v4
	v_mad_i64_i32 v[0:1], s[8:9], v0, s15, v[2:3]
	v_readfirstlane_b32 s8, v112
	s_mov_b32 m0, s8
	v_bfe_u32 v2, v104, 1, 3
	global_load_lds_dwordx4 v[0:1], off
	v_bfe_u32 v0, v104, 4, 2
	v_lshrrev_b32_e32 v1, 1, v104
	v_bitop3_b32 v1, v0, v1, 7 bitop3:0x78
	v_lshlrev_b32_e32 v3, 6, v104
	v_bitop3_b32 v0, v0, v2, 4 bitop3:0x36
	v_lshlrev_b32_e32 v1, 4, v1
	v_and_b32_e32 v3, 0xffffe000, v3
	v_lshlrev_b32_e32 v0, 4, v0
	v_or_b32_e32 v5, v1, v3
	v_or_b32_e32 v2, v0, v3
	v_bitop3_b32 v3, v10, 7, v104 bitop3:0x48
	s_lshl_b32 s21, s11, 7
	v_lshlrev_b32_e32 v64, 4, v3
	v_or_b32_e32 v3, s21, v8
	v_add_u32_e32 v3, v3, v7
	s_lshl_b32 s20, s20, 10
	v_lshlrev_b32_e32 v6, 13, v6
	v_subrev_u32_e32 v3, s20, v3
	v_and_b32_e32 v6, 0x2000, v6
	v_mad_i64_i32 v[70:71], s[8:9], v3, s15, v[66:67]
	v_or_b32_e32 v3, 32, v8
	v_or_b32_e32 v1, v1, v6
	v_or_b32_e32 v0, v0, v6
	v_or_b32_e32 v6, s21, v3
	v_add_u32_e32 v6, v6, v7
	v_subrev_u32_e32 v6, s20, v6
	v_mad_i64_i32 v[72:73], s[8:9], v6, s15, v[66:67]
	v_or_b32_e32 v6, 64, v8
	v_or_b32_e32 v9, s21, v6
	v_add_u32_e32 v9, v9, v7
	v_or_b32_e32 v3, s19, v3
	v_subrev_u32_e32 v9, s20, v9
	v_add_u32_e32 v3, v3, v7
	v_mad_i64_i32 v[74:75], s[8:9], v9, s15, v[66:67]
	v_or_b32_e32 v9, 0x60, v8
	v_mad_i64_i32 v[80:81], s[8:9], v3, s15, v[68:69]
	v_or_b32_e32 v3, s19, v6
	v_or_b32_e32 v10, s21, v9
	v_add_u32_e32 v3, v3, v7
	v_lshlrev_b32_e32 v4, 7, v104
	v_add_u32_e32 v10, v10, v7
	v_or_b32_e32 v8, s19, v8
	v_mad_i64_i32 v[82:83], s[8:9], v3, s15, v[68:69]
	v_or_b32_e32 v3, s19, v9
	v_and_b32_e32 v4, 0x780, v4
	v_subrev_u32_e32 v10, s20, v10
	v_add_u32_e32 v8, v8, v7
	v_add_u32_e32 v3, v3, v7
	v_mad_i64_i32 v[76:77], s[8:9], v10, s15, v[66:67]
	v_mad_i64_i32 v[78:79], s[8:9], v8, s15, v[68:69]
	v_mad_i64_i32 v[84:85], s[8:9], v3, s15, v[68:69]
	s_mov_b32 s20, 0
	v_add_u32_e32 v113, 0x8000, v105
	v_add_u32_e32 v114, 0xc000, v105
	v_add_u32_e32 v115, 0x9000, v105
	v_add_u32_e32 v116, 0xd000, v105
	v_add_u32_e32 v117, 0xa000, v105
	v_add_u32_e32 v118, 0xe000, v105
	v_add_u32_e32 v119, 0xb000, v105
	v_add_u32_e32 v120, 0xf000, v105
	v_add_u32_e32 v121, v5, v4
	v_add_u32_e32 v122, v1, v4
	v_add_u32_e32 v123, v2, v4
	v_add_u32_e32 v124, v0, v4
	v_mov_b32_e32 v0, v65
	v_mov_b32_e32 v1, v65
	v_mov_b32_e32 v2, v65
	v_mov_b32_e32 v3, v65
	v_mov_b32_e32 v16, v65
	v_mov_b32_e32 v17, v65
	v_mov_b32_e32 v18, v65
	v_mov_b32_e32 v19, v65
	v_mov_b32_e32 v32, v65
	v_mov_b32_e32 v33, v65
	v_mov_b32_e32 v34, v65
	v_mov_b32_e32 v35, v65
	v_mov_b32_e32 v48, v65
	v_mov_b32_e32 v49, v65
	v_mov_b32_e32 v50, v65
	v_mov_b32_e32 v51, v65
	v_mov_b32_e32 v4, v65
	v_mov_b32_e32 v5, v65
	v_mov_b32_e32 v6, v65
	v_mov_b32_e32 v7, v65
	v_mov_b32_e32 v20, v65
	v_mov_b32_e32 v21, v65
	v_mov_b32_e32 v22, v65
	v_mov_b32_e32 v23, v65
	v_mov_b32_e32 v36, v65
	v_mov_b32_e32 v37, v65
	v_mov_b32_e32 v38, v65
	v_mov_b32_e32 v39, v65
	v_mov_b32_e32 v52, v65
	v_mov_b32_e32 v53, v65
	v_mov_b32_e32 v54, v65
	v_mov_b32_e32 v55, v65
	v_mov_b32_e32 v8, v65
	v_mov_b32_e32 v9, v65
	v_mov_b32_e32 v10, v65
	v_mov_b32_e32 v11, v65
	v_mov_b32_e32 v24, v65
	v_mov_b32_e32 v25, v65
	v_mov_b32_e32 v26, v65
	v_mov_b32_e32 v27, v65
	v_mov_b32_e32 v40, v65
	v_mov_b32_e32 v41, v65
	v_mov_b32_e32 v42, v65
	v_mov_b32_e32 v43, v65
	v_mov_b32_e32 v56, v65
	v_mov_b32_e32 v57, v65
	v_mov_b32_e32 v58, v65
	v_mov_b32_e32 v59, v65
	v_mov_b32_e32 v12, v65
	v_mov_b32_e32 v13, v65
	v_mov_b32_e32 v14, v65
	v_mov_b32_e32 v15, v65
	v_mov_b32_e32 v28, v65
	v_mov_b32_e32 v29, v65
	v_mov_b32_e32 v30, v65
	v_mov_b32_e32 v31, v65
	v_mov_b32_e32 v44, v65
	v_mov_b32_e32 v45, v65
	v_mov_b32_e32 v46, v65
	v_mov_b32_e32 v47, v65
	v_mov_b32_e32 v60, v65
	v_mov_b32_e32 v61, v65
	v_mov_b32_e32 v62, v65
	v_mov_b32_e32 v63, v65
	v_readlane_b32 s26, v248, 2
	v_readlane_b32 s27, v248, 3
	v_readlane_b32 s73, v248, 59
	v_readlane_b32 s74, v248, 60
	v_readlane_b32 s75, v248, 61
	v_readlane_b32 s76, v248, 62
	v_readlane_b32 s77, v248, 63
	v_readlane_b32 s78, v247, 0
	v_readlane_b32 s79, v247, 1
	v_readlane_b32 s80, v247, 2
	v_readlane_b32 s81, v247, 3
	v_readlane_b32 s82, v247, 4
	v_readlane_b32 s83, v247, 5
	v_readlane_b32 s84, v247, 6
	v_readlane_b32 s85, v247, 7
	s_branch .LBB0_964

; template <bool DB, class AF>
; DEVI void gemm_mainloop(int tid, u16* sA, u16* sB, AF af, const u16* __restrict__ Bt, int ldb, int m0, int n0, int nk,
;                         f32x4 (&acc)[4][4]) {
;   const int lane = tid & 63, w = tid >> 6;
;   const int wm = w >> 1, wn = w & 1, col = lane & 15, quad = lane >> 4;
; #pragma unroll
;   for (int i = 0; i < 4; ++i)
; #pragma unroll
;     for (int j = 0; j < 4; ++j) acc[i][j] = f32x4{0.f, 0.f, 0.f, 0.f};
;   uint4 ra0, ra1, ra2, ra3, rb0, rb1, rb2, rb3;
;   const int lrow = tid >> 3, lkc = (tid & 7) << 3;
;   const u16* bbase = Bt + (size_t)(n0 + lrow) * ldb + lkc;
;     ...
;   if (DB) {
;     const int srow = 8 * w + (lane >> 3);
;     const int spc = lane & 7;
;     ...
;     STAGE_(0, 0)
; template <bool RESB>
; DEVI void phase_resid(const Params& p, unsigned char* smem, const u16* A, const u16* Wt, const float* res, float* ssq) {
;     ...
;   XCD_TILE_LOOP(idx, 256, 8) {
;     GEMM_LANE_VARS
;     const int mt = XCD_TILE_MT(idx, 8), nt_ = XCD_TILE_NT(idx, 8);
;     const int m0 = mt * 128, n0 = nt_ * 128;
;     f32x4 acc[4][4];
;     gemm_mainloop<true>(tid, sA, sB, ARow{A, LDA}, Wt, LDA, m0, n0, 16, acc);
.LBB0_1089:
	v_mov_b32_e32 v105, v210
	s_ashr_i32 s4, s11, 31
	s_lshr_b32 s4, s4, 29
	v_ashrrev_i32_e32 v6, 6, v105
	s_add_i32 s4, s11, s4
	v_lshlrev_b32_e32 v7, 3, v6
	v_bfe_u32 v8, v105, 3, 3
	s_and_b32 s17, s4, -8
	v_or_b32_e32 v9, v7, v8
	s_ashr_i32 s19, s4, 3
	s_or_b32 s18, s17, s13
	v_lshrrev_b32_e32 v10, 1, v9
	s_and_b64 s[4:5], s[2:3], exec
	v_xor_b32_e32 v0, v10, v105
	s_cselect_b32 s4, s18, s19
	v_lshlrev_b32_e32 v0, 4, v0
	s_lshl_b32 s18, s4, 7
	v_and_b32_e32 v64, 0x70, v0
	s_sub_i32 s5, s11, s17
	s_waitcnt lgkmcnt(0)
	v_lshl_add_u64 v[0:1], s[70:71], 0, v[64:65]
	v_add_u32_e32 v4, s18, v9
	s_lshl_b32 s17, s5, 7
	v_mad_i64_i32 v[4:5], s[4:5], v4, s15, v[0:1]
	v_lshlrev_b32_e32 v106, 10, v6
	v_readlane_b32 s72, v247, 10
	v_readfirstlane_b32 s4, v106
	v_readlane_b32 s76, v247, 14
	v_readlane_b32 s77, v247, 15
	s_mov_b32 m0, s4
	v_add_u32_e32 v107, 0x4000, v106
	v_lshl_add_u64 v[2:3], s[76:77], 0, v[64:65]
	global_load_lds_dwordx4 v[4:5], off
	v_add_u32_e32 v4, s17, v9
	v_mad_i64_i32 v[4:5], s[4:5], v4, s15, v[2:3]
	v_readfirstlane_b32 s4, v107
	s_mov_b32 m0, s4
	v_add_u32_e32 v11, 32, v9
	global_load_lds_dwordx4 v[4:5], off
	v_add_u32_e32 v4, s18, v11
	v_mad_i64_i32 v[4:5], s[4:5], v4, s15, v[0:1]
	v_add_u32_e32 v108, 0x1000, v106
	v_add_u32_e32 v109, 0x5000, v106
	v_readfirstlane_b32 s4, v108
	s_mov_b32 m0, s4
	v_add_u32_e32 v110, 0x2000, v106
	global_load_lds_dwordx4 v[4:5], off
	v_add_u32_e32 v4, s17, v11
	v_mad_i64_i32 v[4:5], s[4:5], v4, s15, v[2:3]
	v_readfirstlane_b32 s4, v109
	s_mov_b32 m0, s4
	v_add_u32_e32 v11, 64, v9
	global_load_lds_dwordx4 v[4:5], off
	v_add_u32_e32 v4, s18, v11
	v_mad_i64_i32 v[4:5], s[4:5], v4, s15, v[0:1]
	v_readfirstlane_b32 s4, v110
	s_mov_b32 m0, s4
	v_add_u32_e32 v111, 0x6000, v106
	global_load_lds_dwordx4 v[4:5], off
	v_add_u32_e32 v4, s17, v11
	v_mad_i64_i32 v[4:5], s[4:5], v4, s15, v[2:3]
	v_readfirstlane_b32 s4, v111
	s_mov_b32 m0, s4
	s_nop 0
	v_add_u32_e32 v112, 0x3000, v106
	global_load_lds_dwordx4 v[4:5], off
	v_add_u32_e32 v4, 0x60, v9
	v_add_u32_e32 v5, s18, v4
	v_mad_i64_i32 v[0:1], s[4:5], v5, s15, v[0:1]
	v_readfirstlane_b32 s4, v112
	s_mov_b32 m0, s4
	v_add_u32_e32 v113, 0x7000, v106
	global_load_lds_dwordx4 v[0:1], off
	v_add_u32_e32 v0, s17, v4
	v_mad_i64_i32 v[0:1], s[4:5], v0, s15, v[2:3]
	v_readfirstlane_b32 s4, v113
	s_mov_b32 m0, s4
	v_bfe_u32 v104, v105, 4, 2
	global_load_lds_dwordx4 v[0:1], off
	v_lshrrev_b32_e32 v0, 1, v105
	v_bfe_u32 v1, v105, 1, 3
	v_bitop3_b32 v0, v104, v0, 7 bitop3:0x78
	v_lshlrev_b32_e32 v2, 6, v105
	v_lshlrev_b32_e32 v5, 13, v6
	v_bitop3_b32 v1, v104, v1, 4 bitop3:0x36
	v_lshlrev_b32_e32 v0, 4, v0
	v_and_b32_e32 v2, 0xffffe000, v2
	v_and_b32_e32 v5, 0x2000, v5
	v_lshlrev_b32_e32 v1, 4, v1
	v_or_b32_e32 v4, v0, v2
	v_or_b32_e32 v0, v0, v5
	v_or_b32_e32 v2, v1, v2
	v_or_b32_e32 v1, v1, v5
	v_bitop3_b32 v5, v10, 7, v105 bitop3:0x48
	s_lshl_b32 s20, s11, 7
	v_lshlrev_b32_e32 v64, 4, v5
	v_or_b32_e32 v5, s20, v8
	v_add_u32_e32 v5, v5, v7
	s_lshl_b32 s19, s19, 10
	v_subrev_u32_e32 v5, s19, v5
	v_mad_i64_i32 v[70:71], s[4:5], v5, s15, v[66:67]
	v_or_b32_e32 v5, 32, v8
	v_or_b32_e32 v6, s20, v5
	v_add_u32_e32 v6, v6, v7
	v_subrev_u32_e32 v6, s19, v6
	v_mad_i64_i32 v[72:73], s[4:5], v6, s15, v[66:67]
	v_or_b32_e32 v6, 64, v8
	v_or_b32_e32 v9, s20, v6
	v_add_u32_e32 v9, v9, v7
	v_or_b32_e32 v5, s18, v5
	v_subrev_u32_e32 v9, s19, v9
	v_add_u32_e32 v5, v5, v7
	v_mad_i64_i32 v[74:75], s[4:5], v9, s15, v[66:67]
	v_or_b32_e32 v9, 0x60, v8
	v_mad_i64_i32 v[80:81], s[4:5], v5, s15, v[68:69]
	v_or_b32_e32 v5, s18, v6
	v_or_b32_e32 v10, s20, v9
	v_add_u32_e32 v5, v5, v7
	v_lshlrev_b32_e32 v3, 7, v105
	v_add_u32_e32 v10, v10, v7
	v_or_b32_e32 v8, s18, v8
	v_mad_i64_i32 v[82:83], s[4:5], v5, s15, v[68:69]
	v_or_b32_e32 v5, s18, v9
	v_and_b32_e32 v3, 0x780, v3
	v_subrev_u32_e32 v10, s19, v10
	v_add_u32_e32 v8, v8, v7
	v_add_u32_e32 v5, v5, v7
	v_mad_i64_i32 v[76:77], s[4:5], v10, s15, v[66:67]
	v_mad_i64_i32 v[78:79], s[4:5], v8, s15, v[68:69]
	v_mad_i64_i32 v[84:85], s[4:5], v5, s15, v[68:69]
	s_mov_b32 s19, 0
	v_add_u32_e32 v114, 0x8000, v106
	v_add_u32_e32 v115, 0xc000, v106
	v_add_u32_e32 v116, 0x9000, v106
	v_add_u32_e32 v117, 0xd000, v106
	v_add_u32_e32 v118, 0xa000, v106
	v_add_u32_e32 v119, 0xe000, v106
	v_add_u32_e32 v120, 0xb000, v106
	v_add_u32_e32 v121, 0xf000, v106
	v_add_u32_e32 v122, v4, v3
	v_add_u32_e32 v123, v0, v3
	v_add_u32_e32 v124, v2, v3
	v_add_u32_e32 v125, v1, v3
	v_mov_b32_e32 v0, v65
	v_mov_b32_e32 v1, v65
	v_mov_b32_e32 v2, v65
	v_mov_b32_e32 v3, v65
	v_mov_b32_e32 v16, v65
	v_mov_b32_e32 v17, v65
	v_mov_b32_e32 v18, v65
	v_mov_b32_e32 v19, v65
	v_mov_b32_e32 v32, v65
	v_mov_b32_e32 v33, v65
	v_mov_b32_e32 v34, v65
	v_mov_b32_e32 v35, v65
	v_mov_b32_e32 v48, v65
	v_mov_b32_e32 v49, v65
	v_mov_b32_e32 v50, v65
	v_mov_b32_e32 v51, v65
	v_mov_b32_e32 v4, v65
	v_mov_b32_e32 v5, v65
	v_mov_b32_e32 v6, v65
	v_mov_b32_e32 v7, v65
	v_mov_b32_e32 v20, v65
	v_mov_b32_e32 v21, v65
	v_mov_b32_e32 v22, v65
	v_mov_b32_e32 v23, v65
	v_mov_b32_e32 v36, v65
	v_mov_b32_e32 v37, v65
	v_mov_b32_e32 v38, v65
	v_mov_b32_e32 v39, v65
	v_mov_b32_e32 v52, v65
	v_mov_b32_e32 v53, v65
	v_mov_b32_e32 v54, v65
	v_mov_b32_e32 v55, v65
	v_mov_b32_e32 v8, v65
	v_mov_b32_e32 v9, v65
	v_mov_b32_e32 v10, v65
	v_mov_b32_e32 v11, v65
	v_mov_b32_e32 v24, v65
	v_mov_b32_e32 v25, v65
	v_mov_b32_e32 v26, v65
	v_mov_b32_e32 v27, v65
	v_mov_b32_e32 v40, v65
	v_mov_b32_e32 v41, v65
	v_mov_b32_e32 v42, v65
	v_mov_b32_e32 v43, v65
	v_mov_b32_e32 v56, v65
	v_mov_b32_e32 v57, v65
	v_mov_b32_e32 v58, v65
	v_mov_b32_e32 v59, v65
	v_mov_b32_e32 v12, v65
	v_mov_b32_e32 v13, v65
	v_mov_b32_e32 v14, v65
	v_mov_b32_e32 v15, v65
	v_mov_b32_e32 v28, v65
	v_mov_b32_e32 v29, v65
	v_mov_b32_e32 v30, v65
	v_mov_b32_e32 v31, v65
	v_mov_b32_e32 v44, v65
	v_mov_b32_e32 v45, v65
	v_mov_b32_e32 v46, v65
	v_mov_b32_e32 v47, v65
	v_mov_b32_e32 v60, v65
	v_mov_b32_e32 v61, v65
	v_mov_b32_e32 v62, v65
	v_mov_b32_e32 v63, v65
	v_readlane_b32 s73, v247, 11
	v_readlane_b32 s74, v247, 12
	v_readlane_b32 s75, v247, 13
	v_readlane_b32 s78, v247, 16
	v_readlane_b32 s79, v247, 17
	v_readlane_b32 s80, v247, 18
	v_readlane_b32 s81, v247, 19
	v_readlane_b32 s82, v247, 20
	v_readlane_b32 s83, v247, 21
	v_readlane_b32 s84, v247, 22
	v_readlane_b32 s85, v247, 23
	v_readlane_b32 s86, v247, 24
	v_readlane_b32 s87, v247, 25
	s_branch .LBB0_1091

; template <bool DB, class AF>
; DEVI void gemm_mainloop(int tid, u16* sA, u16* sB, AF af, const u16* __restrict__ Bt, int ldb, int m0, int n0, int nk,
;                         f32x4 (&acc)[4][4]) {
;   const int lane = tid & 63, w = tid >> 6;
;   const int wm = w >> 1, wn = w & 1, col = lane & 15, quad = lane >> 4;
; #pragma unroll
;   for (int i = 0; i < 4; ++i)
; #pragma unroll
;     for (int j = 0; j < 4; ++j) acc[i][j] = f32x4{0.f, 0.f, 0.f, 0.f};
;   uint4 ra0, ra1, ra2, ra3, rb0, rb1, rb2, rb3;
;   const int lrow = tid >> 3, lkc = (tid & 7) << 3;
;   const u16* bbase = Bt + (size_t)(n0 + lrow) * ldb + lkc;
;     ...
;   if (DB) {
;     const int srow = 8 * w + (lane >> 3);
;     const int spc = lane & 7;
;     ...
;     STAGE_(0, 0)
; DEVI void phase_scaled(const Params& p, unsigned char* smem, const u16* A, const u16* Wt, int ntn, const float* ssq, u16* outp, int ldo) {
;     ...
;   XCD_TILE_LOOP(idx, 256, ntn) {
;     GEMM_LANE_VARS
;     const int mt = XCD_TILE_MT(idx, ntn), nt_ = XCD_TILE_NT(idx, ntn);
;     const int m0 = mt * 128, n0 = nt_ * 128;
;     f32x4 acc[4][4];
;     gemm_mainloop<true>(tid, sA, sB, ARow{A, LDA}, Wt, LDA, m0, n0, 16, acc);
.LBB0_1159:
	s_ashr_i32 s8, s11, 31
	v_mov_b32_e32 v104, v210
	s_lshr_b32 s8, s8, 28
	s_add_i32 s19, s11, s8
	v_ashrrev_i32_e32 v6, 6, v104
	s_ashr_i32 s21, s19, 4
	v_lshlrev_b32_e32 v7, 3, v6
	v_bfe_u32 v8, v104, 3, 3
	s_lshl_b32 s8, s21, 3
	v_or_b32_e32 v9, v7, v8
	s_or_b32 s20, s8, s13
	v_lshrrev_b32_e32 v10, 1, v9
	s_and_b64 s[8:9], s[2:3], exec
	v_xor_b32_e32 v0, v10, v104
	s_cselect_b32 s8, s20, s21
	v_lshlrev_b32_e32 v0, 4, v0
	v_readlane_b32 s24, v248, 0
	s_and_b32 s9, s19, 0x1fffff0
	s_lshl_b32 s20, s8, 7
	v_and_b32_e32 v64, 0x70, v0
	v_readlane_b32 s25, v248, 1
	s_sub_i32 s9, s11, s9
	v_add_u32_e32 v4, s20, v9
	v_lshl_add_u64 v[0:1], s[24:25], 0, v[64:65]
	s_lshl_b32 s19, s9, 7
	v_mad_i64_i32 v[4:5], s[8:9], v4, s15, v[0:1]
	v_lshlrev_b32_e32 v105, 10, v6
	v_readlane_b32 s72, v247, 10
	v_readfirstlane_b32 s8, v105
	v_readlane_b32 s78, v247, 16
	v_readlane_b32 s79, v247, 17
	s_mov_b32 m0, s8
	v_add_u32_e32 v106, 0x4000, v105
	v_lshl_add_u64 v[2:3], s[78:79], 0, v[64:65]
	global_load_lds_dwordx4 v[4:5], off
	v_add_u32_e32 v4, s19, v9
	v_mad_i64_i32 v[4:5], s[8:9], v4, s15, v[2:3]
	v_readfirstlane_b32 s8, v106
	s_mov_b32 m0, s8
	v_add_u32_e32 v11, 32, v9
	global_load_lds_dwordx4 v[4:5], off
	v_add_u32_e32 v4, s20, v11
	v_mad_i64_i32 v[4:5], s[8:9], v4, s15, v[0:1]
	v_add_u32_e32 v107, 0x1000, v105
	v_add_u32_e32 v108, 0x5000, v105
	v_readfirstlane_b32 s8, v107
	s_mov_b32 m0, s8
	v_add_u32_e32 v109, 0x2000, v105
	global_load_lds_dwordx4 v[4:5], off
	v_add_u32_e32 v4, s19, v11
	v_mad_i64_i32 v[4:5], s[8:9], v4, s15, v[2:3]
	v_readfirstlane_b32 s8, v108
	s_mov_b32 m0, s8
	v_add_u32_e32 v11, 64, v9
	global_load_lds_dwordx4 v[4:5], off
	v_add_u32_e32 v4, s20, v11
	v_mad_i64_i32 v[4:5], s[8:9], v4, s15, v[0:1]
	v_readfirstlane_b32 s8, v109
	s_mov_b32 m0, s8
	v_add_u32_e32 v110, 0x6000, v105
	global_load_lds_dwordx4 v[4:5], off
	v_add_u32_e32 v4, s19, v11
	v_mad_i64_i32 v[4:5], s[8:9], v4, s15, v[2:3]
	v_readfirstlane_b32 s8, v110
	s_mov_b32 m0, s8
	v_add_u32_e32 v111, 0x3000, v105
	global_load_lds_dwordx4 v[4:5], off
	v_add_u32_e32 v4, 0x60, v9
	v_add_u32_e32 v5, s20, v4
	v_mad_i64_i32 v[0:1], s[8:9], v5, s15, v[0:1]
	v_readfirstlane_b32 s8, v111
	s_mov_b32 m0, s8
	s_nop 0
	v_add_u32_e32 v112, 0x7000, v105
	global_load_lds_dwordx4 v[0:1], off
	v_add_u32_e32 v0, s19, v4
	v_mad_i64_i32 v[0:1], s[8:9], v0, s15, v[2:3]
	v_readfirstlane_b32 s8, v112
	s_mov_b32 m0, s8
	v_bfe_u32 v2, v104, 1, 3
	global_load_lds_dwordx4 v[0:1], off
	v_bfe_u32 v0, v104, 4, 2
	v_lshrrev_b32_e32 v1, 1, v104
	v_bitop3_b32 v1, v0, v1, 7 bitop3:0x78
	v_lshlrev_b32_e32 v3, 6, v104
	v_bitop3_b32 v0, v0, v2, 4 bitop3:0x36
	v_lshlrev_b32_e32 v1, 4, v1
	v_and_b32_e32 v3, 0xffffe000, v3
	v_lshlrev_b32_e32 v0, 4, v0
	v_or_b32_e32 v5, v1, v3
	v_or_b32_e32 v2, v0, v3
	v_bitop3_b32 v3, v10, 7, v104 bitop3:0x48
	s_lshl_b32 s22, s11, 7
	v_lshlrev_b32_e32 v64, 4, v3
	v_or_b32_e32 v3, s22, v8
	v_add_u32_e32 v3, v3, v7
	s_lshl_b32 s21, s21, 11
	v_lshlrev_b32_e32 v6, 13, v6
	v_subrev_u32_e32 v3, s21, v3
	v_and_b32_e32 v6, 0x2000, v6
	v_mad_i64_i32 v[70:71], s[8:9], v3, s15, v[66:67]
	v_or_b32_e32 v3, 32, v8
	v_or_b32_e32 v1, v1, v6
	v_or_b32_e32 v0, v0, v6
	v_or_b32_e32 v6, s22, v3
	v_add_u32_e32 v6, v6, v7
	v_subrev_u32_e32 v6, s21, v6
	v_mad_i64_i32 v[72:73], s[8:9], v6, s15, v[66:67]
	v_or_b32_e32 v6, 64, v8
	v_or_b32_e32 v9, s22, v6
	v_add_u32_e32 v9, v9, v7
	v_or_b32_e32 v3, s20, v3
	v_subrev_u32_e32 v9, s21, v9
	v_add_u32_e32 v3, v3, v7
	v_mad_i64_i32 v[74:75], s[8:9], v9, s15, v[66:67]
	v_or_b32_e32 v9, 0x60, v8
	v_mad_i64_i32 v[80:81], s[8:9], v3, s15, v[68:69]
	v_or_b32_e32 v3, s20, v6
	v_or_b32_e32 v10, s22, v9
	v_add_u32_e32 v3, v3, v7
	v_lshlrev_b32_e32 v4, 7, v104
	v_add_u32_e32 v10, v10, v7
	v_or_b32_e32 v8, s20, v8
	v_mad_i64_i32 v[82:83], s[8:9], v3, s15, v[68:69]
	v_or_b32_e32 v3, s20, v9
	v_and_b32_e32 v4, 0x780, v4
	v_subrev_u32_e32 v10, s21, v10
	v_add_u32_e32 v8, v8, v7
	v_add_u32_e32 v3, v3, v7
	v_mad_i64_i32 v[76:77], s[8:9], v10, s15, v[66:67]
	v_mad_i64_i32 v[78:79], s[8:9], v8, s15, v[68:69]
	v_mad_i64_i32 v[84:85], s[8:9], v3, s15, v[68:69]
	s_mov_b32 s21, 0
	v_add_u32_e32 v113, 0x8000, v105
	v_add_u32_e32 v114, 0xc000, v105
	v_add_u32_e32 v115, 0x9000, v105
	v_add_u32_e32 v116, 0xd000, v105
	v_add_u32_e32 v117, 0xa000, v105
	v_add_u32_e32 v118, 0xe000, v105
	v_add_u32_e32 v119, 0xb000, v105
	v_add_u32_e32 v120, 0xf000, v105
	v_add_u32_e32 v121, v5, v4
	v_add_u32_e32 v122, v1, v4
	v_add_u32_e32 v123, v2, v4
	v_add_u32_e32 v124, v0, v4
	v_mov_b32_e32 v0, v65
	v_mov_b32_e32 v1, v65
	v_mov_b32_e32 v2, v65
	v_mov_b32_e32 v3, v65
	v_mov_b32_e32 v16, v65
	v_mov_b32_e32 v17, v65
	v_mov_b32_e32 v18, v65
	v_mov_b32_e32 v19, v65
	v_mov_b32_e32 v32, v65
	v_mov_b32_e32 v33, v65
	v_mov_b32_e32 v34, v65
	v_mov_b32_e32 v35, v65
	v_mov_b32_e32 v48, v65
	v_mov_b32_e32 v49, v65
	v_mov_b32_e32 v50, v65
	v_mov_b32_e32 v51, v65
	v_mov_b32_e32 v4, v65
	v_mov_b32_e32 v5, v65
	v_mov_b32_e32 v6, v65
	v_mov_b32_e32 v7, v65
	v_mov_b32_e32 v20, v65
	v_mov_b32_e32 v21, v65
	v_mov_b32_e32 v22, v65
	v_mov_b32_e32 v23, v65
	v_mov_b32_e32 v36, v65
	v_mov_b32_e32 v37, v65
	v_mov_b32_e32 v38, v65
	v_mov_b32_e32 v39, v65
	v_mov_b32_e32 v52, v65
	v_mov_b32_e32 v53, v65
	v_mov_b32_e32 v54, v65
	v_mov_b32_e32 v55, v65
	v_mov_b32_e32 v8, v65
	v_mov_b32_e32 v9, v65
	v_mov_b32_e32 v10, v65
	v_mov_b32_e32 v11, v65
	v_mov_b32_e32 v24, v65
	v_mov_b32_e32 v25, v65
	v_mov_b32_e32 v26, v65
	v_mov_b32_e32 v27, v65
	v_mov_b32_e32 v40, v65
	v_mov_b32_e32 v41, v65
	v_mov_b32_e32 v42, v65
	v_mov_b32_e32 v43, v65
	v_mov_b32_e32 v56, v65
	v_mov_b32_e32 v57, v65
	v_mov_b32_e32 v58, v65
	v_mov_b32_e32 v59, v65
	v_mov_b32_e32 v12, v65
	v_mov_b32_e32 v13, v65
	v_mov_b32_e32 v14, v65
	v_mov_b32_e32 v15, v65
	v_mov_b32_e32 v28, v65
	v_mov_b32_e32 v29, v65
	v_mov_b32_e32 v30, v65
	v_mov_b32_e32 v31, v65
	v_mov_b32_e32 v44, v65
	v_mov_b32_e32 v45, v65
	v_mov_b32_e32 v46, v65
	v_mov_b32_e32 v47, v65
	v_mov_b32_e32 v60, v65
	v_mov_b32_e32 v61, v65
	v_mov_b32_e32 v62, v65
	v_mov_b32_e32 v63, v65
	v_readlane_b32 s26, v248, 2
	v_readlane_b32 s27, v248, 3
	v_readlane_b32 s73, v247, 11
	v_readlane_b32 s74, v247, 12
	v_readlane_b32 s75, v247, 13
	v_readlane_b32 s76, v247, 14
	v_readlane_b32 s77, v247, 15
	v_readlane_b32 s80, v247, 18
	v_readlane_b32 s81, v247, 19
	v_readlane_b32 s82, v247, 20
	v_readlane_b32 s83, v247, 21
	v_readlane_b32 s84, v247, 22
	v_readlane_b32 s85, v247, 23
	v_readlane_b32 s86, v247, 24
	v_readlane_b32 s87, v247, 25
	s_branch .LBB0_1161
